# GEMM K-loops: per B-column-fragment, the four row fragments' accumulators in turn, each with its two K-halves chained back to back (B operand pair reused across 8 MFMAs)
# baseline (speedup 1.0000x reference)
.LBB0_260:
	v_add_u32_e32 v168, 0x10000, v232
	v_add_u32_e32 v180, 0x14000, v232
	v_lshl_add_u64 v[224:225], v[222:223], 0, s[62:63]
	s_add_i32 m0, s35, 0xc000
	s_waitcnt lgkmcnt(0)
	ds_read_b128 v[148:151], v207
	ds_read_b128 v[164:167], v207 offset:1024
	ds_read_b128 v[144:147], v207 offset:2048
	ds_read_b128 v[160:163], v207 offset:3072
	ds_read_b128 v[140:143], v207 offset:4096
	ds_read_b128 v[156:159], v207 offset:5120
	ds_read_b128 v[136:139], v207 offset:6144
	ds_read_b128 v[152:155], v207 offset:7168
	ds_read_b128 v[184:187], v168
	ds_read_b128 v[188:191], v168 offset:1024
	ds_read_b128 v[192:195], v168 offset:2048
	ds_read_b128 v[196:199], v168 offset:3072
	ds_read_b128 v[168:171], v180
	ds_read_b128 v[172:175], v180 offset:1024
	ds_read_b128 v[176:179], v180 offset:2048
	ds_read_b128 v[180:183], v180 offset:3072
	global_load_lds_dwordx4 v[224:225], off
	v_lshl_add_u64 v[224:225], v[220:221], 0, s[62:63]
	s_add_i32 m0, s35, 0xe000
	s_nop 0
	global_load_lds_dwordx4 v[224:225], off
	s_waitcnt vmcnt(8)
	s_waitcnt lgkmcnt(0)
	s_barrier
	s_setprio 1
	s_waitcnt lgkmcnt(0)
	v_mfma_f32_16x16x32_bf16 v[132:135], v[184:187], v[148:151], v[132:135]
	v_mfma_f32_16x16x32_bf16 v[132:135], v[188:191], v[164:167], v[132:135]
	v_mfma_f32_16x16x32_bf16 v[116:119], v[184:187], v[144:147], v[116:119]
	v_mfma_f32_16x16x32_bf16 v[116:119], v[188:191], v[160:163], v[116:119]
	v_mfma_f32_16x16x32_bf16 v[100:103], v[184:187], v[140:143], v[100:103]
	v_mfma_f32_16x16x32_bf16 v[100:103], v[188:191], v[156:159], v[100:103]
	v_mfma_f32_16x16x32_bf16 v[84:87], v[184:187], v[136:139], v[84:87]
	v_mfma_f32_16x16x32_bf16 v[84:87], v[188:191], v[152:155], v[84:87]
	v_mfma_f32_16x16x32_bf16 v[128:131], v[192:195], v[148:151], v[128:131]
	v_mfma_f32_16x16x32_bf16 v[128:131], v[196:199], v[164:167], v[128:131]
	v_mfma_f32_16x16x32_bf16 v[112:115], v[192:195], v[144:147], v[112:115]
	v_mfma_f32_16x16x32_bf16 v[112:115], v[196:199], v[160:163], v[112:115]
	v_mfma_f32_16x16x32_bf16 v[96:99], v[192:195], v[140:143], v[96:99]
	v_mfma_f32_16x16x32_bf16 v[96:99], v[196:199], v[156:159], v[96:99]
	v_mfma_f32_16x16x32_bf16 v[80:83], v[192:195], v[136:139], v[80:83]
	v_mfma_f32_16x16x32_bf16 v[80:83], v[196:199], v[152:155], v[80:83]
	s_setprio 0
	s_setprio 1
	v_mfma_f32_16x16x32_bf16 v[124:127], v[168:171], v[148:151], v[124:127]
	v_mfma_f32_16x16x32_bf16 v[124:127], v[172:175], v[164:167], v[124:127]
	v_mfma_f32_16x16x32_bf16 v[108:111], v[168:171], v[144:147], v[108:111]
	v_mfma_f32_16x16x32_bf16 v[108:111], v[172:175], v[160:163], v[108:111]
	v_mfma_f32_16x16x32_bf16 v[92:95], v[168:171], v[140:143], v[92:95]
	v_mfma_f32_16x16x32_bf16 v[92:95], v[172:175], v[156:159], v[92:95]
	v_mfma_f32_16x16x32_bf16 v[76:79], v[168:171], v[136:139], v[76:79]
	v_mfma_f32_16x16x32_bf16 v[76:79], v[172:175], v[152:155], v[76:79]
	v_mfma_f32_16x16x32_bf16 v[120:123], v[176:179], v[148:151], v[120:123]
	v_mfma_f32_16x16x32_bf16 v[120:123], v[180:183], v[164:167], v[120:123]
	v_mfma_f32_16x16x32_bf16 v[104:107], v[176:179], v[144:147], v[104:107]
	v_mfma_f32_16x16x32_bf16 v[104:107], v[180:183], v[160:163], v[104:107]
	v_mfma_f32_16x16x32_bf16 v[88:91], v[176:179], v[140:143], v[88:91]
	v_mfma_f32_16x16x32_bf16 v[88:91], v[180:183], v[156:159], v[88:91]
	v_mfma_f32_16x16x32_bf16 v[72:75], v[176:179], v[136:139], v[72:75]
	v_mfma_f32_16x16x32_bf16 v[72:75], v[180:183], v[152:155], v[72:75]
	s_setprio 0
	s_barrier
	v_cndmask_b32_e64 v204, 0, 1, s[60:61]
	v_cmp_ne_u32_e64 s[50:51], 1, v204
	s_andn2_b64 vcc, exec, s[60:61]
	s_cbranch_vccnz .LBB0_262
	ds_read_b128 v[148:151], v207 offset:16384
	ds_read_b128 v[164:167], v207 offset:17408
	ds_read_b128 v[144:147], v207 offset:18432
	ds_read_b128 v[160:163], v207 offset:19456
	ds_read_b128 v[140:143], v207 offset:20480
	ds_read_b128 v[156:159], v207 offset:21504
	ds_read_b128 v[136:139], v207 offset:22528
	ds_read_b128 v[152:155], v207 offset:23552
.LBB0_262:
	s_add_u32 s12, s58, s62
	s_addc_u32 s13, s59, s63
	s_add_u32 s14, s12, 0x100
	s_addc_u32 s15, s13, 0
	s_add_u32 s75, s26, s62
	s_addc_u32 s76, s27, s63
	s_cmpk_eq_i32 s62, 0xf00
	s_cselect_b64 s[52:53], -1, 0
	s_and_b64 s[12:13], s[52:53], exec
	s_cselect_b32 s13, s21, s76
	s_cselect_b32 s12, s73, s75
	s_mov_b32 m0, s38
	s_cselect_b32 s15, s25, s15
	s_cselect_b32 s14, s33, s14
	v_lshl_add_u64 v[224:225], s[12:13], 0, v[208:209]
	s_add_u32 s76, s12, 0x80000
	global_load_lds_dwordx4 v[224:225], off
	v_lshl_add_u64 v[226:227], s[12:13], 0, v[212:213]
	s_mov_b32 m0, s39
	s_addc_u32 s77, s13, 0
	global_load_lds_dwordx4 v[226:227], off
	v_lshl_add_u64 v[228:229], s[76:77], 0, v[208:209]
	s_mov_b32 m0, s40
	v_lshl_add_u64 v[230:231], s[14:15], 0, v[210:211]
	global_load_lds_dwordx4 v[228:229], off
	v_lshl_add_u64 v[228:229], s[76:77], 0, v[212:213]
	s_mov_b32 m0, s41
	s_and_b64 vcc, exec, s[50:51]
	global_load_lds_dwordx4 v[228:229], off
	v_lshl_add_u64 v[228:229], s[14:15], 0, v[4:5]
	s_mov_b32 m0, s35
	s_nop 0
	global_load_lds_dwordx4 v[228:229], off
	s_mov_b32 m0, s43
	s_nop 0
	global_load_lds_dwordx4 v[230:231], off
	s_waitcnt vmcnt(8)
	s_waitcnt lgkmcnt(0)
	s_barrier
	s_cbranch_vccnz .LBB0_264
	s_setprio 1
	s_waitcnt lgkmcnt(0)
	v_mfma_f32_16x16x32_bf16 v[68:71], v[184:187], v[148:151], v[68:71]
	v_mfma_f32_16x16x32_bf16 v[68:71], v[188:191], v[164:167], v[68:71]
	v_mfma_f32_16x16x32_bf16 v[52:55], v[184:187], v[144:147], v[52:55]
	v_mfma_f32_16x16x32_bf16 v[52:55], v[188:191], v[160:163], v[52:55]
	v_mfma_f32_16x16x32_bf16 v[36:39], v[184:187], v[140:143], v[36:39]
	v_mfma_f32_16x16x32_bf16 v[36:39], v[188:191], v[156:159], v[36:39]
	v_mfma_f32_16x16x32_bf16 v[20:23], v[184:187], v[136:139], v[20:23]
	v_mfma_f32_16x16x32_bf16 v[20:23], v[188:191], v[152:155], v[20:23]
	v_mfma_f32_16x16x32_bf16 v[64:67], v[192:195], v[148:151], v[64:67]
	v_mfma_f32_16x16x32_bf16 v[64:67], v[196:199], v[164:167], v[64:67]
	v_mfma_f32_16x16x32_bf16 v[48:51], v[192:195], v[144:147], v[48:51]
	v_mfma_f32_16x16x32_bf16 v[48:51], v[196:199], v[160:163], v[48:51]
	v_mfma_f32_16x16x32_bf16 v[32:35], v[192:195], v[140:143], v[32:35]
	v_mfma_f32_16x16x32_bf16 v[32:35], v[196:199], v[156:159], v[32:35]
	v_mfma_f32_16x16x32_bf16 v[16:19], v[192:195], v[136:139], v[16:19]
	v_mfma_f32_16x16x32_bf16 v[16:19], v[196:199], v[152:155], v[16:19]
	s_setprio 0
	s_setprio 1
	v_mfma_f32_16x16x32_bf16 v[60:63], v[168:171], v[148:151], v[60:63]
	v_mfma_f32_16x16x32_bf16 v[60:63], v[172:175], v[164:167], v[60:63]
	v_mfma_f32_16x16x32_bf16 v[44:47], v[168:171], v[144:147], v[44:47]
	v_mfma_f32_16x16x32_bf16 v[44:47], v[172:175], v[160:163], v[44:47]
	v_mfma_f32_16x16x32_bf16 v[28:31], v[168:171], v[140:143], v[28:31]
	v_mfma_f32_16x16x32_bf16 v[28:31], v[172:175], v[156:159], v[28:31]
	v_mfma_f32_16x16x32_bf16 v[12:15], v[168:171], v[136:139], v[12:15]
	v_mfma_f32_16x16x32_bf16 v[12:15], v[172:175], v[152:155], v[12:15]
	v_mfma_f32_16x16x32_bf16 v[56:59], v[176:179], v[148:151], v[56:59]
	v_mfma_f32_16x16x32_bf16 v[56:59], v[180:183], v[164:167], v[56:59]
	v_mfma_f32_16x16x32_bf16 v[40:43], v[176:179], v[144:147], v[40:43]
	v_mfma_f32_16x16x32_bf16 v[40:43], v[180:183], v[160:163], v[40:43]
	v_mfma_f32_16x16x32_bf16 v[24:27], v[176:179], v[140:143], v[24:27]
	v_mfma_f32_16x16x32_bf16 v[24:27], v[180:183], v[156:159], v[24:27]
	v_mfma_f32_16x16x32_bf16 v[8:11], v[176:179], v[136:139], v[8:11]
	v_mfma_f32_16x16x32_bf16 v[8:11], v[180:183], v[152:155], v[8:11]
	s_setprio 0
.LBB0_264:
	s_barrier
	v_cndmask_b32_e64 v241, v219, 0, s[52:53]
	v_cndmask_b32_e64 v240, v218, v2, s[52:53]
	v_lshl_add_u64 v[240:241], s[14:15], 0, v[240:241]
	s_mov_b32 m0, s45
	v_add_u32_e32 v168, 0x18000, v232
	v_add_u32_e32 v180, 0x1c000, v232
	v_lshl_add_u64 v[242:243], v[240:241], 0, v[4:5]
	s_waitcnt lgkmcnt(0)
	ds_read_b128 v[148:151], v207 offset:32768
	ds_read_b128 v[164:167], v207 offset:33792
	ds_read_b128 v[144:147], v207 offset:34816
	ds_read_b128 v[160:163], v207 offset:35840
	ds_read_b128 v[140:143], v207 offset:36864
	ds_read_b128 v[156:159], v207 offset:37888
	ds_read_b128 v[136:139], v207 offset:38912
	ds_read_b128 v[152:155], v207 offset:39936
	ds_read_b128 v[184:187], v168
	ds_read_b128 v[188:191], v168 offset:1024
	ds_read_b128 v[192:195], v168 offset:2048
	ds_read_b128 v[196:199], v168 offset:3072
	ds_read_b128 v[168:171], v180
	ds_read_b128 v[172:175], v180 offset:1024
	ds_read_b128 v[176:179], v180 offset:2048
	ds_read_b128 v[180:183], v180 offset:3072
	global_load_lds_dwordx4 v[242:243], off
	v_lshl_add_u64 v[240:241], v[240:241], 0, v[210:211]
	s_mov_b32 m0, s47
	s_nop 0
	global_load_lds_dwordx4 v[240:241], off
	s_waitcnt vmcnt(8)
	s_waitcnt lgkmcnt(0)
	s_barrier
	s_setprio 1
	s_waitcnt lgkmcnt(0)
	v_mfma_f32_16x16x32_bf16 v[132:135], v[184:187], v[148:151], v[132:135]
	v_mfma_f32_16x16x32_bf16 v[132:135], v[188:191], v[164:167], v[132:135]
	v_mfma_f32_16x16x32_bf16 v[116:119], v[184:187], v[144:147], v[116:119]
	v_mfma_f32_16x16x32_bf16 v[116:119], v[188:191], v[160:163], v[116:119]
	v_mfma_f32_16x16x32_bf16 v[100:103], v[184:187], v[140:143], v[100:103]
	v_mfma_f32_16x16x32_bf16 v[100:103], v[188:191], v[156:159], v[100:103]
	v_mfma_f32_16x16x32_bf16 v[84:87], v[184:187], v[136:139], v[84:87]
	v_mfma_f32_16x16x32_bf16 v[84:87], v[188:191], v[152:155], v[84:87]
	v_mfma_f32_16x16x32_bf16 v[128:131], v[192:195], v[148:151], v[128:131]
	v_mfma_f32_16x16x32_bf16 v[128:131], v[196:199], v[164:167], v[128:131]
	v_mfma_f32_16x16x32_bf16 v[112:115], v[192:195], v[144:147], v[112:115]
	v_mfma_f32_16x16x32_bf16 v[112:115], v[196:199], v[160:163], v[112:115]
	v_mfma_f32_16x16x32_bf16 v[96:99], v[192:195], v[140:143], v[96:99]
	v_mfma_f32_16x16x32_bf16 v[96:99], v[196:199], v[156:159], v[96:99]
	v_mfma_f32_16x16x32_bf16 v[80:83], v[192:195], v[136:139], v[80:83]
	v_mfma_f32_16x16x32_bf16 v[80:83], v[196:199], v[152:155], v[80:83]
	s_setprio 0
	s_setprio 1
	v_mfma_f32_16x16x32_bf16 v[124:127], v[168:171], v[148:151], v[124:127]
	v_mfma_f32_16x16x32_bf16 v[124:127], v[172:175], v[164:167], v[124:127]
	v_mfma_f32_16x16x32_bf16 v[108:111], v[168:171], v[144:147], v[108:111]
	v_mfma_f32_16x16x32_bf16 v[108:111], v[172:175], v[160:163], v[108:111]
	v_mfma_f32_16x16x32_bf16 v[92:95], v[168:171], v[140:143], v[92:95]
	v_mfma_f32_16x16x32_bf16 v[92:95], v[172:175], v[156:159], v[92:95]
	v_mfma_f32_16x16x32_bf16 v[76:79], v[168:171], v[136:139], v[76:79]
	v_mfma_f32_16x16x32_bf16 v[76:79], v[172:175], v[152:155], v[76:79]
	v_mfma_f32_16x16x32_bf16 v[120:123], v[176:179], v[148:151], v[120:123]
	v_mfma_f32_16x16x32_bf16 v[120:123], v[180:183], v[164:167], v[120:123]
	v_mfma_f32_16x16x32_bf16 v[104:107], v[176:179], v[144:147], v[104:107]
	v_mfma_f32_16x16x32_bf16 v[104:107], v[180:183], v[160:163], v[104:107]
	v_mfma_f32_16x16x32_bf16 v[88:91], v[176:179], v[140:143], v[88:91]
	v_mfma_f32_16x16x32_bf16 v[88:91], v[180:183], v[156:159], v[88:91]
	v_mfma_f32_16x16x32_bf16 v[72:75], v[176:179], v[136:139], v[72:75]
	v_mfma_f32_16x16x32_bf16 v[72:75], v[180:183], v[152:155], v[72:75]
	s_setprio 0
	s_barrier
	s_and_b64 vcc, exec, s[50:51]
	s_cbranch_vccnz .LBB0_266
	ds_read_b128 v[148:151], v207 offset:49152
	ds_read_b128 v[164:167], v207 offset:50176
	ds_read_b128 v[144:147], v207 offset:51200
	ds_read_b128 v[160:163], v207 offset:52224
	ds_read_b128 v[140:143], v207 offset:53248
	ds_read_b128 v[156:159], v207 offset:54272
	ds_read_b128 v[136:139], v207 offset:55296
	ds_read_b128 v[152:155], v207 offset:56320
.LBB0_266:
	s_mov_b32 m0, s64
	v_lshl_add_u64 v[224:225], v[224:225], 0, s[0:1]
	s_add_u32 s12, s12, 0x80080
	global_load_lds_dwordx4 v[224:225], off
	v_lshl_add_u64 v[224:225], v[226:227], 0, s[0:1]
	s_mov_b32 m0, s65
	s_addc_u32 s13, s13, 0
	global_load_lds_dwordx4 v[224:225], off
	v_lshl_add_u64 v[224:225], s[12:13], 0, v[208:209]
	s_mov_b32 m0, s68
	s_and_b64 vcc, exec, s[50:51]
	global_load_lds_dwordx4 v[224:225], off
	v_lshl_add_u64 v[224:225], s[12:13], 0, v[212:213]
	s_mov_b32 m0, s69
	s_nop 0
	global_load_lds_dwordx4 v[224:225], off
	v_lshl_add_u64 v[224:225], v[228:229], 0, s[0:1]
	s_mov_b32 m0, s66
	s_nop 0
	global_load_lds_dwordx4 v[224:225], off
	v_lshl_add_u64 v[224:225], v[230:231], 0, s[0:1]
	s_mov_b32 m0, s67
	s_nop 0
	global_load_lds_dwordx4 v[224:225], off
	s_waitcnt vmcnt(8)
	s_waitcnt lgkmcnt(0)
	s_barrier
	s_cbranch_vccnz .LBB0_259
	s_setprio 1
	s_waitcnt lgkmcnt(0)
	v_mfma_f32_16x16x32_bf16 v[68:71], v[184:187], v[148:151], v[68:71]
	v_mfma_f32_16x16x32_bf16 v[68:71], v[188:191], v[164:167], v[68:71]
	v_mfma_f32_16x16x32_bf16 v[52:55], v[184:187], v[144:147], v[52:55]
	v_mfma_f32_16x16x32_bf16 v[52:55], v[188:191], v[160:163], v[52:55]
	v_mfma_f32_16x16x32_bf16 v[36:39], v[184:187], v[140:143], v[36:39]
	v_mfma_f32_16x16x32_bf16 v[36:39], v[188:191], v[156:159], v[36:39]
	v_mfma_f32_16x16x32_bf16 v[20:23], v[184:187], v[136:139], v[20:23]
	v_mfma_f32_16x16x32_bf16 v[20:23], v[188:191], v[152:155], v[20:23]
	v_mfma_f32_16x16x32_bf16 v[64:67], v[192:195], v[148:151], v[64:67]
	v_mfma_f32_16x16x32_bf16 v[64:67], v[196:199], v[164:167], v[64:67]
	v_mfma_f32_16x16x32_bf16 v[48:51], v[192:195], v[144:147], v[48:51]
	v_mfma_f32_16x16x32_bf16 v[48:51], v[196:199], v[160:163], v[48:51]
	v_mfma_f32_16x16x32_bf16 v[32:35], v[192:195], v[140:143], v[32:35]
	v_mfma_f32_16x16x32_bf16 v[32:35], v[196:199], v[156:159], v[32:35]
	v_mfma_f32_16x16x32_bf16 v[16:19], v[192:195], v[136:139], v[16:19]
	v_mfma_f32_16x16x32_bf16 v[16:19], v[196:199], v[152:155], v[16:19]
	s_setprio 0
	s_setprio 1
	v_mfma_f32_16x16x32_bf16 v[60:63], v[168:171], v[148:151], v[60:63]
	v_mfma_f32_16x16x32_bf16 v[60:63], v[172:175], v[164:167], v[60:63]
	v_mfma_f32_16x16x32_bf16 v[44:47], v[168:171], v[144:147], v[44:47]
	v_mfma_f32_16x16x32_bf16 v[44:47], v[172:175], v[160:163], v[44:47]
	v_mfma_f32_16x16x32_bf16 v[28:31], v[168:171], v[140:143], v[28:31]
	v_mfma_f32_16x16x32_bf16 v[28:31], v[172:175], v[156:159], v[28:31]
	v_mfma_f32_16x16x32_bf16 v[12:15], v[168:171], v[136:139], v[12:15]
	v_mfma_f32_16x16x32_bf16 v[12:15], v[172:175], v[152:155], v[12:15]
	v_mfma_f32_16x16x32_bf16 v[56:59], v[176:179], v[148:151], v[56:59]
	v_mfma_f32_16x16x32_bf16 v[56:59], v[180:183], v[164:167], v[56:59]
	v_mfma_f32_16x16x32_bf16 v[40:43], v[176:179], v[144:147], v[40:43]
	v_mfma_f32_16x16x32_bf16 v[40:43], v[180:183], v[160:163], v[40:43]
	v_mfma_f32_16x16x32_bf16 v[24:27], v[176:179], v[140:143], v[24:27]
	v_mfma_f32_16x16x32_bf16 v[24:27], v[180:183], v[156:159], v[24:27]
	v_mfma_f32_16x16x32_bf16 v[8:11], v[176:179], v[136:139], v[8:11]
	v_mfma_f32_16x16x32_bf16 v[8:11], v[180:183], v[152:155], v[8:11]
	s_setprio 0
	s_branch .LBB0_259

.LBB0_369:
	v_add_u32_e32 v168, 0x10000, v232
	v_add_u32_e32 v180, 0x14000, v232
	v_lshl_add_u64 v[224:225], v[222:223], 0, s[60:61]
	s_add_i32 m0, s9, 0xc000
	s_waitcnt lgkmcnt(0)
	ds_read_b128 v[148:151], v207
	ds_read_b128 v[164:167], v207 offset:1024
	ds_read_b128 v[144:147], v207 offset:2048
	ds_read_b128 v[160:163], v207 offset:3072
	ds_read_b128 v[140:143], v207 offset:4096
	ds_read_b128 v[156:159], v207 offset:5120
	ds_read_b128 v[136:139], v207 offset:6144
	ds_read_b128 v[152:155], v207 offset:7168
	ds_read_b128 v[184:187], v168
	ds_read_b128 v[188:191], v168 offset:1024
	ds_read_b128 v[192:195], v168 offset:2048
	ds_read_b128 v[196:199], v168 offset:3072
	ds_read_b128 v[168:171], v180
	ds_read_b128 v[172:175], v180 offset:1024
	ds_read_b128 v[176:179], v180 offset:2048
	ds_read_b128 v[180:183], v180 offset:3072
	global_load_lds_dwordx4 v[224:225], off
	v_lshl_add_u64 v[224:225], v[220:221], 0, s[60:61]
	s_add_i32 m0, s9, 0xe000
	s_nop 0
	global_load_lds_dwordx4 v[224:225], off
	s_waitcnt vmcnt(8)
	s_waitcnt lgkmcnt(0)
	s_barrier
	s_setprio 1
	s_waitcnt lgkmcnt(0)
	v_mfma_f32_16x16x32_bf16 v[132:135], v[184:187], v[148:151], v[132:135]
	v_mfma_f32_16x16x32_bf16 v[132:135], v[188:191], v[164:167], v[132:135]
	v_mfma_f32_16x16x32_bf16 v[124:127], v[184:187], v[144:147], v[124:127]
	v_mfma_f32_16x16x32_bf16 v[124:127], v[188:191], v[160:163], v[124:127]
	v_mfma_f32_16x16x32_bf16 v[108:111], v[184:187], v[140:143], v[108:111]
	v_mfma_f32_16x16x32_bf16 v[108:111], v[188:191], v[156:159], v[108:111]
	v_mfma_f32_16x16x32_bf16 v[92:95], v[184:187], v[136:139], v[92:95]
	v_mfma_f32_16x16x32_bf16 v[92:95], v[188:191], v[152:155], v[92:95]
	v_mfma_f32_16x16x32_bf16 v[128:131], v[192:195], v[148:151], v[128:131]
	v_mfma_f32_16x16x32_bf16 v[128:131], v[196:199], v[164:167], v[128:131]
	v_mfma_f32_16x16x32_bf16 v[120:123], v[192:195], v[144:147], v[120:123]
	v_mfma_f32_16x16x32_bf16 v[120:123], v[196:199], v[160:163], v[120:123]
	v_mfma_f32_16x16x32_bf16 v[104:107], v[192:195], v[140:143], v[104:107]
	v_mfma_f32_16x16x32_bf16 v[104:107], v[196:199], v[156:159], v[104:107]
	v_mfma_f32_16x16x32_bf16 v[88:91], v[192:195], v[136:139], v[88:91]
	v_mfma_f32_16x16x32_bf16 v[88:91], v[196:199], v[152:155], v[88:91]
	s_setprio 0
	s_setprio 1
	v_mfma_f32_16x16x32_bf16 v[116:119], v[168:171], v[148:151], v[116:119]
	v_mfma_f32_16x16x32_bf16 v[116:119], v[172:175], v[164:167], v[116:119]
	v_mfma_f32_16x16x32_bf16 v[100:103], v[168:171], v[144:147], v[100:103]
	v_mfma_f32_16x16x32_bf16 v[100:103], v[172:175], v[160:163], v[100:103]
	v_mfma_f32_16x16x32_bf16 v[84:87], v[168:171], v[140:143], v[84:87]
	v_mfma_f32_16x16x32_bf16 v[84:87], v[172:175], v[156:159], v[84:87]
	v_mfma_f32_16x16x32_bf16 v[76:79], v[168:171], v[136:139], v[76:79]
	v_mfma_f32_16x16x32_bf16 v[76:79], v[172:175], v[152:155], v[76:79]
	v_mfma_f32_16x16x32_bf16 v[112:115], v[176:179], v[148:151], v[112:115]
	v_mfma_f32_16x16x32_bf16 v[112:115], v[180:183], v[164:167], v[112:115]
	v_mfma_f32_16x16x32_bf16 v[96:99], v[176:179], v[144:147], v[96:99]
	v_mfma_f32_16x16x32_bf16 v[96:99], v[180:183], v[160:163], v[96:99]
	v_mfma_f32_16x16x32_bf16 v[80:83], v[176:179], v[140:143], v[80:83]
	v_mfma_f32_16x16x32_bf16 v[80:83], v[180:183], v[156:159], v[80:83]
	v_mfma_f32_16x16x32_bf16 v[72:75], v[176:179], v[136:139], v[72:75]
	v_mfma_f32_16x16x32_bf16 v[72:75], v[180:183], v[152:155], v[72:75]
	s_setprio 0
	s_barrier
	v_cndmask_b32_e64 v204, 0, 1, s[58:59]
	v_cmp_ne_u32_e64 s[50:51], 1, v204
	s_andn2_b64 vcc, exec, s[58:59]
	s_cbranch_vccnz .LBB0_371
	ds_read_b128 v[148:151], v207 offset:16384
	ds_read_b128 v[164:167], v207 offset:17408
	ds_read_b128 v[144:147], v207 offset:18432
	ds_read_b128 v[160:163], v207 offset:19456
	ds_read_b128 v[140:143], v207 offset:20480
	ds_read_b128 v[156:159], v207 offset:21504
	ds_read_b128 v[136:139], v207 offset:22528
	ds_read_b128 v[152:155], v207 offset:23552
.LBB0_371:
	s_add_u32 s12, s24, s60
	s_addc_u32 s13, s25, s61
	s_add_u32 s14, s12, 0x100
	s_addc_u32 s15, s13, 0
	s_add_u32 s73, s26, s60
	s_addc_u32 s74, s27, s61
	s_cmpk_eq_i32 s60, 0xf00
	s_cselect_b64 s[52:53], -1, 0
	s_and_b64 s[12:13], s[52:53], exec
	s_cselect_b32 s13, s37, s74
	s_cselect_b32 s12, s43, s73
	s_mov_b32 m0, s38
	s_cselect_b32 s15, s7, s15
	s_cselect_b32 s14, s33, s14
	v_lshl_add_u64 v[224:225], s[12:13], 0, v[208:209]
	s_add_u32 s74, s12, 0x80000
	global_load_lds_dwordx4 v[224:225], off
	v_lshl_add_u64 v[226:227], s[12:13], 0, v[212:213]
	s_mov_b32 m0, s39
	s_addc_u32 s75, s13, 0
	global_load_lds_dwordx4 v[226:227], off
	v_lshl_add_u64 v[228:229], s[74:75], 0, v[208:209]
	s_mov_b32 m0, s40
	v_lshl_add_u64 v[230:231], s[14:15], 0, v[210:211]
	global_load_lds_dwordx4 v[228:229], off
	v_lshl_add_u64 v[228:229], s[74:75], 0, v[212:213]
	s_mov_b32 m0, s41
	s_and_b64 vcc, exec, s[50:51]
	global_load_lds_dwordx4 v[228:229], off
	v_lshl_add_u64 v[228:229], s[14:15], 0, v[4:5]
	s_mov_b32 m0, s9
	s_nop 0
	global_load_lds_dwordx4 v[228:229], off
	s_mov_b32 m0, s47
	s_nop 0
	global_load_lds_dwordx4 v[230:231], off
	s_waitcnt vmcnt(8)
	s_waitcnt lgkmcnt(0)
	s_barrier
	s_cbranch_vccnz .LBB0_373
	s_setprio 1
	s_waitcnt lgkmcnt(0)
	v_mfma_f32_16x16x32_bf16 v[68:71], v[184:187], v[148:151], v[68:71]
	v_mfma_f32_16x16x32_bf16 v[68:71], v[188:191], v[164:167], v[68:71]
	v_mfma_f32_16x16x32_bf16 v[52:55], v[184:187], v[144:147], v[52:55]
	v_mfma_f32_16x16x32_bf16 v[52:55], v[188:191], v[160:163], v[52:55]
	v_mfma_f32_16x16x32_bf16 v[36:39], v[184:187], v[140:143], v[36:39]
	v_mfma_f32_16x16x32_bf16 v[36:39], v[188:191], v[156:159], v[36:39]
	v_mfma_f32_16x16x32_bf16 v[20:23], v[184:187], v[136:139], v[20:23]
	v_mfma_f32_16x16x32_bf16 v[20:23], v[188:191], v[152:155], v[20:23]
	v_mfma_f32_16x16x32_bf16 v[64:67], v[192:195], v[148:151], v[64:67]
	v_mfma_f32_16x16x32_bf16 v[64:67], v[196:199], v[164:167], v[64:67]
	v_mfma_f32_16x16x32_bf16 v[48:51], v[192:195], v[144:147], v[48:51]
	v_mfma_f32_16x16x32_bf16 v[48:51], v[196:199], v[160:163], v[48:51]
	v_mfma_f32_16x16x32_bf16 v[32:35], v[192:195], v[140:143], v[32:35]
	v_mfma_f32_16x16x32_bf16 v[32:35], v[196:199], v[156:159], v[32:35]
	v_mfma_f32_16x16x32_bf16 v[16:19], v[192:195], v[136:139], v[16:19]
	v_mfma_f32_16x16x32_bf16 v[16:19], v[196:199], v[152:155], v[16:19]
	s_setprio 0
	s_setprio 1
	v_mfma_f32_16x16x32_bf16 v[60:63], v[168:171], v[148:151], v[60:63]
	v_mfma_f32_16x16x32_bf16 v[60:63], v[172:175], v[164:167], v[60:63]
	v_mfma_f32_16x16x32_bf16 v[44:47], v[168:171], v[144:147], v[44:47]
	v_mfma_f32_16x16x32_bf16 v[44:47], v[172:175], v[160:163], v[44:47]
	v_mfma_f32_16x16x32_bf16 v[28:31], v[168:171], v[140:143], v[28:31]
	v_mfma_f32_16x16x32_bf16 v[28:31], v[172:175], v[156:159], v[28:31]
	v_mfma_f32_16x16x32_bf16 v[12:15], v[168:171], v[136:139], v[12:15]
	v_mfma_f32_16x16x32_bf16 v[12:15], v[172:175], v[152:155], v[12:15]
	v_mfma_f32_16x16x32_bf16 v[56:59], v[176:179], v[148:151], v[56:59]
	v_mfma_f32_16x16x32_bf16 v[56:59], v[180:183], v[164:167], v[56:59]
	v_mfma_f32_16x16x32_bf16 v[40:43], v[176:179], v[144:147], v[40:43]
	v_mfma_f32_16x16x32_bf16 v[40:43], v[180:183], v[160:163], v[40:43]
	v_mfma_f32_16x16x32_bf16 v[24:27], v[176:179], v[140:143], v[24:27]
	v_mfma_f32_16x16x32_bf16 v[24:27], v[180:183], v[156:159], v[24:27]
	v_mfma_f32_16x16x32_bf16 v[8:11], v[176:179], v[136:139], v[8:11]
	v_mfma_f32_16x16x32_bf16 v[8:11], v[180:183], v[152:155], v[8:11]
	s_setprio 0
.LBB0_373:
	s_barrier
	v_cndmask_b32_e64 v241, v219, 0, s[52:53]
	v_cndmask_b32_e64 v240, v218, v2, s[52:53]
	v_lshl_add_u64 v[240:241], s[14:15], 0, v[240:241]
	s_mov_b32 m0, s62
	v_add_u32_e32 v168, 0x18000, v232
	v_add_u32_e32 v180, 0x1c000, v232
	v_lshl_add_u64 v[242:243], v[240:241], 0, v[4:5]
	s_waitcnt lgkmcnt(0)
	ds_read_b128 v[148:151], v207 offset:32768
	ds_read_b128 v[164:167], v207 offset:33792
	ds_read_b128 v[144:147], v207 offset:34816
	ds_read_b128 v[160:163], v207 offset:35840
	ds_read_b128 v[140:143], v207 offset:36864
	ds_read_b128 v[156:159], v207 offset:37888
	ds_read_b128 v[136:139], v207 offset:38912
	ds_read_b128 v[152:155], v207 offset:39936
	ds_read_b128 v[184:187], v168
	ds_read_b128 v[188:191], v168 offset:1024
	ds_read_b128 v[192:195], v168 offset:2048
	ds_read_b128 v[196:199], v168 offset:3072
	ds_read_b128 v[168:171], v180
	ds_read_b128 v[172:175], v180 offset:1024
	ds_read_b128 v[176:179], v180 offset:2048
	ds_read_b128 v[180:183], v180 offset:3072
	global_load_lds_dwordx4 v[242:243], off
	v_lshl_add_u64 v[240:241], v[240:241], 0, v[210:211]
	s_mov_b32 m0, s63
	s_nop 0
	global_load_lds_dwordx4 v[240:241], off
	s_waitcnt vmcnt(8)
	s_waitcnt lgkmcnt(0)
	s_barrier
	s_setprio 1
	s_waitcnt lgkmcnt(0)
	v_mfma_f32_16x16x32_bf16 v[132:135], v[184:187], v[148:151], v[132:135]
	v_mfma_f32_16x16x32_bf16 v[132:135], v[188:191], v[164:167], v[132:135]
	v_mfma_f32_16x16x32_bf16 v[124:127], v[184:187], v[144:147], v[124:127]
	v_mfma_f32_16x16x32_bf16 v[124:127], v[188:191], v[160:163], v[124:127]
	v_mfma_f32_16x16x32_bf16 v[108:111], v[184:187], v[140:143], v[108:111]
	v_mfma_f32_16x16x32_bf16 v[108:111], v[188:191], v[156:159], v[108:111]
	v_mfma_f32_16x16x32_bf16 v[92:95], v[184:187], v[136:139], v[92:95]
	v_mfma_f32_16x16x32_bf16 v[92:95], v[188:191], v[152:155], v[92:95]
	v_mfma_f32_16x16x32_bf16 v[128:131], v[192:195], v[148:151], v[128:131]
	v_mfma_f32_16x16x32_bf16 v[128:131], v[196:199], v[164:167], v[128:131]
	v_mfma_f32_16x16x32_bf16 v[120:123], v[192:195], v[144:147], v[120:123]
	v_mfma_f32_16x16x32_bf16 v[120:123], v[196:199], v[160:163], v[120:123]
	v_mfma_f32_16x16x32_bf16 v[104:107], v[192:195], v[140:143], v[104:107]
	v_mfma_f32_16x16x32_bf16 v[104:107], v[196:199], v[156:159], v[104:107]
	v_mfma_f32_16x16x32_bf16 v[88:91], v[192:195], v[136:139], v[88:91]
	v_mfma_f32_16x16x32_bf16 v[88:91], v[196:199], v[152:155], v[88:91]
	s_setprio 0
	s_setprio 1
	v_mfma_f32_16x16x32_bf16 v[116:119], v[168:171], v[148:151], v[116:119]
	v_mfma_f32_16x16x32_bf16 v[116:119], v[172:175], v[164:167], v[116:119]
	v_mfma_f32_16x16x32_bf16 v[100:103], v[168:171], v[144:147], v[100:103]
	v_mfma_f32_16x16x32_bf16 v[100:103], v[172:175], v[160:163], v[100:103]
	v_mfma_f32_16x16x32_bf16 v[84:87], v[168:171], v[140:143], v[84:87]
	v_mfma_f32_16x16x32_bf16 v[84:87], v[172:175], v[156:159], v[84:87]
	v_mfma_f32_16x16x32_bf16 v[76:79], v[168:171], v[136:139], v[76:79]
	v_mfma_f32_16x16x32_bf16 v[76:79], v[172:175], v[152:155], v[76:79]
	v_mfma_f32_16x16x32_bf16 v[112:115], v[176:179], v[148:151], v[112:115]
	v_mfma_f32_16x16x32_bf16 v[112:115], v[180:183], v[164:167], v[112:115]
	v_mfma_f32_16x16x32_bf16 v[96:99], v[176:179], v[144:147], v[96:99]
	v_mfma_f32_16x16x32_bf16 v[96:99], v[180:183], v[160:163], v[96:99]
	v_mfma_f32_16x16x32_bf16 v[80:83], v[176:179], v[140:143], v[80:83]
	v_mfma_f32_16x16x32_bf16 v[80:83], v[180:183], v[156:159], v[80:83]
	v_mfma_f32_16x16x32_bf16 v[72:75], v[176:179], v[136:139], v[72:75]
	v_mfma_f32_16x16x32_bf16 v[72:75], v[180:183], v[152:155], v[72:75]
	s_setprio 0
	s_barrier
	s_and_b64 vcc, exec, s[50:51]
	s_cbranch_vccnz .LBB0_375
	ds_read_b128 v[148:151], v207 offset:49152
	ds_read_b128 v[164:167], v207 offset:50176
	ds_read_b128 v[144:147], v207 offset:51200
	ds_read_b128 v[160:163], v207 offset:52224
	ds_read_b128 v[140:143], v207 offset:53248
	ds_read_b128 v[156:159], v207 offset:54272
	ds_read_b128 v[136:139], v207 offset:55296
	ds_read_b128 v[152:155], v207 offset:56320

.LBB0_559:
	v_add_u32_e32 v168, 0x10000, v240
	v_add_u32_e32 v180, 0x14000, v240
	v_lshl_add_u64 v[226:227], v[224:225], 0, s[64:65]
	s_add_i32 m0, s38, 0xc000
	s_waitcnt lgkmcnt(0)
	ds_read_b128 v[148:151], v239
	ds_read_b128 v[164:167], v239 offset:1024
	ds_read_b128 v[144:147], v239 offset:2048
	ds_read_b128 v[160:163], v239 offset:3072
	ds_read_b128 v[140:143], v239 offset:4096
	ds_read_b128 v[156:159], v239 offset:5120
	ds_read_b128 v[136:139], v239 offset:6144
	ds_read_b128 v[152:155], v239 offset:7168
	ds_read_b128 v[184:187], v168
	ds_read_b128 v[188:191], v168 offset:1024
	ds_read_b128 v[192:195], v168 offset:2048
	ds_read_b128 v[196:199], v168 offset:3072
	ds_read_b128 v[168:171], v180
	ds_read_b128 v[172:175], v180 offset:1024
	ds_read_b128 v[176:179], v180 offset:2048
	ds_read_b128 v[180:183], v180 offset:3072
	global_load_lds_dwordx4 v[226:227], off
	v_lshl_add_u64 v[226:227], v[222:223], 0, s[64:65]
	s_add_i32 m0, s38, 0xe000
	s_nop 0
	global_load_lds_dwordx4 v[226:227], off
	s_waitcnt vmcnt(8)
	s_waitcnt lgkmcnt(0)
	s_barrier
	s_setprio 1
	s_waitcnt lgkmcnt(0)
	v_mfma_f32_16x16x32_bf16 v[132:135], v[184:187], v[148:151], v[132:135]
	v_mfma_f32_16x16x32_bf16 v[132:135], v[188:191], v[164:167], v[132:135]
	v_mfma_f32_16x16x32_bf16 v[116:119], v[184:187], v[144:147], v[116:119]
	v_mfma_f32_16x16x32_bf16 v[116:119], v[188:191], v[160:163], v[116:119]
	v_mfma_f32_16x16x32_bf16 v[100:103], v[184:187], v[140:143], v[100:103]
	v_mfma_f32_16x16x32_bf16 v[100:103], v[188:191], v[156:159], v[100:103]
	v_mfma_f32_16x16x32_bf16 v[84:87], v[184:187], v[136:139], v[84:87]
	v_mfma_f32_16x16x32_bf16 v[84:87], v[188:191], v[152:155], v[84:87]
	v_mfma_f32_16x16x32_bf16 v[128:131], v[192:195], v[148:151], v[128:131]
	v_mfma_f32_16x16x32_bf16 v[128:131], v[196:199], v[164:167], v[128:131]
	v_mfma_f32_16x16x32_bf16 v[112:115], v[192:195], v[144:147], v[112:115]
	v_mfma_f32_16x16x32_bf16 v[112:115], v[196:199], v[160:163], v[112:115]
	v_mfma_f32_16x16x32_bf16 v[96:99], v[192:195], v[140:143], v[96:99]
	v_mfma_f32_16x16x32_bf16 v[96:99], v[196:199], v[156:159], v[96:99]
	v_mfma_f32_16x16x32_bf16 v[80:83], v[192:195], v[136:139], v[80:83]
	v_mfma_f32_16x16x32_bf16 v[80:83], v[196:199], v[152:155], v[80:83]
	s_setprio 0
	s_setprio 1
	v_mfma_f32_16x16x32_bf16 v[124:127], v[168:171], v[148:151], v[124:127]
	v_mfma_f32_16x16x32_bf16 v[124:127], v[172:175], v[164:167], v[124:127]
	v_mfma_f32_16x16x32_bf16 v[108:111], v[168:171], v[144:147], v[108:111]
	v_mfma_f32_16x16x32_bf16 v[108:111], v[172:175], v[160:163], v[108:111]
	v_mfma_f32_16x16x32_bf16 v[92:95], v[168:171], v[140:143], v[92:95]
	v_mfma_f32_16x16x32_bf16 v[92:95], v[172:175], v[156:159], v[92:95]
	v_mfma_f32_16x16x32_bf16 v[76:79], v[168:171], v[136:139], v[76:79]
	v_mfma_f32_16x16x32_bf16 v[76:79], v[172:175], v[152:155], v[76:79]
	v_mfma_f32_16x16x32_bf16 v[120:123], v[176:179], v[148:151], v[120:123]
	v_mfma_f32_16x16x32_bf16 v[120:123], v[180:183], v[164:167], v[120:123]
	v_mfma_f32_16x16x32_bf16 v[104:107], v[176:179], v[144:147], v[104:107]
	v_mfma_f32_16x16x32_bf16 v[104:107], v[180:183], v[160:163], v[104:107]
	v_mfma_f32_16x16x32_bf16 v[88:91], v[176:179], v[140:143], v[88:91]
	v_mfma_f32_16x16x32_bf16 v[88:91], v[180:183], v[156:159], v[88:91]
	v_mfma_f32_16x16x32_bf16 v[72:75], v[176:179], v[136:139], v[72:75]
	v_mfma_f32_16x16x32_bf16 v[72:75], v[180:183], v[152:155], v[72:75]
	s_setprio 0
	s_barrier
	v_cndmask_b32_e64 v204, 0, 1, s[62:63]
	v_cmp_ne_u32_e64 s[50:51], 1, v204
	s_andn2_b64 vcc, exec, s[62:63]
	s_cbranch_vccnz .LBB0_561
	ds_read_b128 v[148:151], v239 offset:16384
	ds_read_b128 v[164:167], v239 offset:17408
	ds_read_b128 v[144:147], v239 offset:18432
	ds_read_b128 v[160:163], v239 offset:19456
	ds_read_b128 v[140:143], v239 offset:20480
	ds_read_b128 v[156:159], v239 offset:21504
	ds_read_b128 v[136:139], v239 offset:22528
	ds_read_b128 v[152:155], v239 offset:23552
.LBB0_561:
	s_add_u32 s12, s60, s64
	s_addc_u32 s13, s61, s65
	s_add_u32 s14, s12, 0x100
	s_addc_u32 s15, s13, 0
	s_add_u32 s79, s26, s64
	s_addc_u32 s80, s27, s65
	s_cmpk_eq_i32 s64, 0x300
	s_cselect_b64 s[52:53], -1, 0
	s_and_b64 s[12:13], s[52:53], exec
	s_cselect_b32 s13, s17, s80
	s_cselect_b32 s12, s35, s79
	s_mov_b32 m0, s39
	s_cselect_b32 s15, s21, s15
	s_cselect_b32 s14, s33, s14
	v_lshl_add_u64 v[226:227], s[12:13], 0, v[4:5]
	s_add_u32 s80, s12, 0x20000
	global_load_lds_dwordx4 v[226:227], off
	v_lshl_add_u64 v[228:229], s[12:13], 0, v[208:209]
	s_mov_b32 m0, s40
	s_addc_u32 s81, s13, 0
	global_load_lds_dwordx4 v[228:229], off
	v_lshl_add_u64 v[230:231], s[80:81], 0, v[4:5]
	s_mov_b32 m0, s41
	v_lshl_add_u64 v[232:233], s[14:15], 0, v[208:209]
	global_load_lds_dwordx4 v[230:231], off
	v_lshl_add_u64 v[230:231], s[80:81], 0, v[208:209]
	s_mov_b32 m0, s47
	s_and_b64 vcc, exec, s[50:51]
	global_load_lds_dwordx4 v[230:231], off
	v_lshl_add_u64 v[230:231], s[14:15], 0, v[4:5]
	s_mov_b32 m0, s38
	s_nop 0
	global_load_lds_dwordx4 v[230:231], off
	s_mov_b32 m0, s59
	s_nop 0
	global_load_lds_dwordx4 v[232:233], off
	s_waitcnt vmcnt(8)
	s_waitcnt lgkmcnt(0)
	s_barrier
	s_cbranch_vccnz .LBB0_563
	s_setprio 1
	s_waitcnt lgkmcnt(0)
	v_mfma_f32_16x16x32_bf16 v[68:71], v[184:187], v[148:151], v[68:71]
	v_mfma_f32_16x16x32_bf16 v[68:71], v[188:191], v[164:167], v[68:71]
	v_mfma_f32_16x16x32_bf16 v[52:55], v[184:187], v[144:147], v[52:55]
	v_mfma_f32_16x16x32_bf16 v[52:55], v[188:191], v[160:163], v[52:55]
	v_mfma_f32_16x16x32_bf16 v[36:39], v[184:187], v[140:143], v[36:39]
	v_mfma_f32_16x16x32_bf16 v[36:39], v[188:191], v[156:159], v[36:39]
	v_mfma_f32_16x16x32_bf16 v[20:23], v[184:187], v[136:139], v[20:23]
	v_mfma_f32_16x16x32_bf16 v[20:23], v[188:191], v[152:155], v[20:23]
	v_mfma_f32_16x16x32_bf16 v[64:67], v[192:195], v[148:151], v[64:67]
	v_mfma_f32_16x16x32_bf16 v[64:67], v[196:199], v[164:167], v[64:67]
	v_mfma_f32_16x16x32_bf16 v[48:51], v[192:195], v[144:147], v[48:51]
	v_mfma_f32_16x16x32_bf16 v[48:51], v[196:199], v[160:163], v[48:51]
	v_mfma_f32_16x16x32_bf16 v[32:35], v[192:195], v[140:143], v[32:35]
	v_mfma_f32_16x16x32_bf16 v[32:35], v[196:199], v[156:159], v[32:35]
	v_mfma_f32_16x16x32_bf16 v[16:19], v[192:195], v[136:139], v[16:19]
	v_mfma_f32_16x16x32_bf16 v[16:19], v[196:199], v[152:155], v[16:19]
	s_setprio 0
	s_setprio 1
	v_mfma_f32_16x16x32_bf16 v[60:63], v[168:171], v[148:151], v[60:63]
	v_mfma_f32_16x16x32_bf16 v[60:63], v[172:175], v[164:167], v[60:63]
	v_mfma_f32_16x16x32_bf16 v[44:47], v[168:171], v[144:147], v[44:47]
	v_mfma_f32_16x16x32_bf16 v[44:47], v[172:175], v[160:163], v[44:47]
	v_mfma_f32_16x16x32_bf16 v[28:31], v[168:171], v[140:143], v[28:31]
	v_mfma_f32_16x16x32_bf16 v[28:31], v[172:175], v[156:159], v[28:31]
	v_mfma_f32_16x16x32_bf16 v[12:15], v[168:171], v[136:139], v[12:15]
	v_mfma_f32_16x16x32_bf16 v[12:15], v[172:175], v[152:155], v[12:15]
	v_mfma_f32_16x16x32_bf16 v[56:59], v[176:179], v[148:151], v[56:59]
	v_mfma_f32_16x16x32_bf16 v[56:59], v[180:183], v[164:167], v[56:59]
	v_mfma_f32_16x16x32_bf16 v[40:43], v[176:179], v[144:147], v[40:43]
	v_mfma_f32_16x16x32_bf16 v[40:43], v[180:183], v[160:163], v[40:43]
	v_mfma_f32_16x16x32_bf16 v[24:27], v[176:179], v[140:143], v[24:27]
	v_mfma_f32_16x16x32_bf16 v[24:27], v[180:183], v[156:159], v[24:27]
	v_mfma_f32_16x16x32_bf16 v[8:11], v[176:179], v[136:139], v[8:11]
	v_mfma_f32_16x16x32_bf16 v[8:11], v[180:183], v[152:155], v[8:11]
	s_setprio 0
.LBB0_563:
	s_barrier
	v_cndmask_b32_e64 v243, v221, 0, s[52:53]
	v_cndmask_b32_e64 v242, v220, v2, s[52:53]
	v_lshl_add_u64 v[242:243], s[14:15], 0, v[242:243]
	s_mov_b32 m0, s66
	v_add_u32_e32 v168, 0x18000, v240
	v_add_u32_e32 v180, 0x1c000, v240
	v_lshl_add_u64 v[204:205], v[242:243], 0, v[4:5]
	s_waitcnt lgkmcnt(0)
	ds_read_b128 v[148:151], v239 offset:32768
	ds_read_b128 v[164:167], v239 offset:33792
	ds_read_b128 v[144:147], v239 offset:34816
	ds_read_b128 v[160:163], v239 offset:35840
	ds_read_b128 v[140:143], v239 offset:36864
	ds_read_b128 v[156:159], v239 offset:37888
	ds_read_b128 v[136:139], v239 offset:38912
	ds_read_b128 v[152:155], v239 offset:39936
	ds_read_b128 v[184:187], v168
	ds_read_b128 v[188:191], v168 offset:1024
	ds_read_b128 v[192:195], v168 offset:2048
	ds_read_b128 v[196:199], v168 offset:3072
	ds_read_b128 v[168:171], v180
	ds_read_b128 v[172:175], v180 offset:1024
	ds_read_b128 v[176:179], v180 offset:2048
	ds_read_b128 v[180:183], v180 offset:3072
	global_load_lds_dwordx4 v[204:205], off
	v_lshl_add_u64 v[204:205], v[242:243], 0, v[208:209]
	s_mov_b32 m0, s67
	s_nop 0
	global_load_lds_dwordx4 v[204:205], off
	s_waitcnt vmcnt(8)
	s_waitcnt lgkmcnt(0)
	s_barrier
	s_setprio 1
	s_waitcnt lgkmcnt(0)
	v_mfma_f32_16x16x32_bf16 v[132:135], v[184:187], v[148:151], v[132:135]
	v_mfma_f32_16x16x32_bf16 v[132:135], v[188:191], v[164:167], v[132:135]
	v_mfma_f32_16x16x32_bf16 v[116:119], v[184:187], v[144:147], v[116:119]
	v_mfma_f32_16x16x32_bf16 v[116:119], v[188:191], v[160:163], v[116:119]
	v_mfma_f32_16x16x32_bf16 v[100:103], v[184:187], v[140:143], v[100:103]
	v_mfma_f32_16x16x32_bf16 v[100:103], v[188:191], v[156:159], v[100:103]
	v_mfma_f32_16x16x32_bf16 v[84:87], v[184:187], v[136:139], v[84:87]
	v_mfma_f32_16x16x32_bf16 v[84:87], v[188:191], v[152:155], v[84:87]
	v_mfma_f32_16x16x32_bf16 v[128:131], v[192:195], v[148:151], v[128:131]
	v_mfma_f32_16x16x32_bf16 v[128:131], v[196:199], v[164:167], v[128:131]
	v_mfma_f32_16x16x32_bf16 v[112:115], v[192:195], v[144:147], v[112:115]
	v_mfma_f32_16x16x32_bf16 v[112:115], v[196:199], v[160:163], v[112:115]
	v_mfma_f32_16x16x32_bf16 v[96:99], v[192:195], v[140:143], v[96:99]
	v_mfma_f32_16x16x32_bf16 v[96:99], v[196:199], v[156:159], v[96:99]
	v_mfma_f32_16x16x32_bf16 v[80:83], v[192:195], v[136:139], v[80:83]
	v_mfma_f32_16x16x32_bf16 v[80:83], v[196:199], v[152:155], v[80:83]
	s_setprio 0
	s_setprio 1
	v_mfma_f32_16x16x32_bf16 v[124:127], v[168:171], v[148:151], v[124:127]
	v_mfma_f32_16x16x32_bf16 v[124:127], v[172:175], v[164:167], v[124:127]
	v_mfma_f32_16x16x32_bf16 v[108:111], v[168:171], v[144:147], v[108:111]
	v_mfma_f32_16x16x32_bf16 v[108:111], v[172:175], v[160:163], v[108:111]
	v_mfma_f32_16x16x32_bf16 v[92:95], v[168:171], v[140:143], v[92:95]
	v_mfma_f32_16x16x32_bf16 v[92:95], v[172:175], v[156:159], v[92:95]
	v_mfma_f32_16x16x32_bf16 v[76:79], v[168:171], v[136:139], v[76:79]
	v_mfma_f32_16x16x32_bf16 v[76:79], v[172:175], v[152:155], v[76:79]
	v_mfma_f32_16x16x32_bf16 v[120:123], v[176:179], v[148:151], v[120:123]
	v_mfma_f32_16x16x32_bf16 v[120:123], v[180:183], v[164:167], v[120:123]
	v_mfma_f32_16x16x32_bf16 v[104:107], v[176:179], v[144:147], v[104:107]
	v_mfma_f32_16x16x32_bf16 v[104:107], v[180:183], v[160:163], v[104:107]
	v_mfma_f32_16x16x32_bf16 v[88:91], v[176:179], v[140:143], v[88:91]
	v_mfma_f32_16x16x32_bf16 v[88:91], v[180:183], v[156:159], v[88:91]
	v_mfma_f32_16x16x32_bf16 v[72:75], v[176:179], v[136:139], v[72:75]
	v_mfma_f32_16x16x32_bf16 v[72:75], v[180:183], v[152:155], v[72:75]
	s_setprio 0
	s_barrier
	s_and_b64 vcc, exec, s[50:51]
	s_cbranch_vccnz .LBB0_565
	ds_read_b128 v[148:151], v239 offset:49152
	ds_read_b128 v[164:167], v239 offset:50176
	ds_read_b128 v[144:147], v239 offset:51200
	ds_read_b128 v[160:163], v239 offset:52224
	ds_read_b128 v[140:143], v239 offset:53248
	ds_read_b128 v[156:159], v239 offset:54272
	ds_read_b128 v[136:139], v239 offset:55296
	ds_read_b128 v[152:155], v239 offset:56320
.LBB0_565:
	s_mov_b32 m0, s70
	v_lshl_add_u64 v[204:205], v[226:227], 0, s[0:1]
	s_add_u32 s12, s12, 0x20080
	global_load_lds_dwordx4 v[204:205], off
	v_lshl_add_u64 v[204:205], v[228:229], 0, s[0:1]
	s_mov_b32 m0, s71
	s_addc_u32 s13, s13, 0
	global_load_lds_dwordx4 v[204:205], off
	v_lshl_add_u64 v[204:205], s[12:13], 0, v[4:5]
	s_mov_b32 m0, s74
	s_and_b64 vcc, exec, s[50:51]
	global_load_lds_dwordx4 v[204:205], off
	v_lshl_add_u64 v[204:205], s[12:13], 0, v[208:209]
	s_mov_b32 m0, s75
	s_nop 0
	global_load_lds_dwordx4 v[204:205], off
	v_lshl_add_u64 v[204:205], v[230:231], 0, s[0:1]
	s_mov_b32 m0, s72
	s_nop 0
	global_load_lds_dwordx4 v[204:205], off
	v_lshl_add_u64 v[204:205], v[232:233], 0, s[0:1]
	s_mov_b32 m0, s73
	s_nop 0
	global_load_lds_dwordx4 v[204:205], off
	s_waitcnt vmcnt(8)
	s_waitcnt lgkmcnt(0)
	s_barrier
	s_cbranch_vccnz .LBB0_558
	s_setprio 1
	s_waitcnt lgkmcnt(0)
	v_mfma_f32_16x16x32_bf16 v[68:71], v[184:187], v[148:151], v[68:71]
	v_mfma_f32_16x16x32_bf16 v[68:71], v[188:191], v[164:167], v[68:71]
	v_mfma_f32_16x16x32_bf16 v[52:55], v[184:187], v[144:147], v[52:55]
	v_mfma_f32_16x16x32_bf16 v[52:55], v[188:191], v[160:163], v[52:55]
	v_mfma_f32_16x16x32_bf16 v[36:39], v[184:187], v[140:143], v[36:39]
	v_mfma_f32_16x16x32_bf16 v[36:39], v[188:191], v[156:159], v[36:39]
	v_mfma_f32_16x16x32_bf16 v[20:23], v[184:187], v[136:139], v[20:23]
	v_mfma_f32_16x16x32_bf16 v[20:23], v[188:191], v[152:155], v[20:23]
	v_mfma_f32_16x16x32_bf16 v[64:67], v[192:195], v[148:151], v[64:67]
	v_mfma_f32_16x16x32_bf16 v[64:67], v[196:199], v[164:167], v[64:67]
	v_mfma_f32_16x16x32_bf16 v[48:51], v[192:195], v[144:147], v[48:51]
	v_mfma_f32_16x16x32_bf16 v[48:51], v[196:199], v[160:163], v[48:51]
	v_mfma_f32_16x16x32_bf16 v[32:35], v[192:195], v[140:143], v[32:35]
	v_mfma_f32_16x16x32_bf16 v[32:35], v[196:199], v[156:159], v[32:35]
	v_mfma_f32_16x16x32_bf16 v[16:19], v[192:195], v[136:139], v[16:19]
	v_mfma_f32_16x16x32_bf16 v[16:19], v[196:199], v[152:155], v[16:19]
	s_setprio 0
	s_setprio 1
	v_mfma_f32_16x16x32_bf16 v[60:63], v[168:171], v[148:151], v[60:63]
	v_mfma_f32_16x16x32_bf16 v[60:63], v[172:175], v[164:167], v[60:63]
	v_mfma_f32_16x16x32_bf16 v[44:47], v[168:171], v[144:147], v[44:47]
	v_mfma_f32_16x16x32_bf16 v[44:47], v[172:175], v[160:163], v[44:47]
	v_mfma_f32_16x16x32_bf16 v[28:31], v[168:171], v[140:143], v[28:31]
	v_mfma_f32_16x16x32_bf16 v[28:31], v[172:175], v[156:159], v[28:31]
	v_mfma_f32_16x16x32_bf16 v[12:15], v[168:171], v[136:139], v[12:15]
	v_mfma_f32_16x16x32_bf16 v[12:15], v[172:175], v[152:155], v[12:15]
	v_mfma_f32_16x16x32_bf16 v[56:59], v[176:179], v[148:151], v[56:59]
	v_mfma_f32_16x16x32_bf16 v[56:59], v[180:183], v[164:167], v[56:59]
	v_mfma_f32_16x16x32_bf16 v[40:43], v[176:179], v[144:147], v[40:43]
	v_mfma_f32_16x16x32_bf16 v[40:43], v[180:183], v[160:163], v[40:43]
	v_mfma_f32_16x16x32_bf16 v[24:27], v[176:179], v[140:143], v[24:27]
	v_mfma_f32_16x16x32_bf16 v[24:27], v[180:183], v[156:159], v[24:27]
	v_mfma_f32_16x16x32_bf16 v[8:11], v[176:179], v[136:139], v[8:11]
	v_mfma_f32_16x16x32_bf16 v[8:11], v[180:183], v[152:155], v[8:11]
	s_setprio 0
	s_branch .LBB0_558

.LBB0_620:
	s_add_u32 s12, s42, 0xfffe0080
	s_addc_u32 s13, s43, -1
	s_cmp_eq_u32 s57, 4
	s_cselect_b32 s15, s17, s13
	s_cselect_b32 s14, s33, s12
	s_cselect_b32 s13, s11, s27
	s_cselect_b32 s12, s37, s26
	s_add_i32 s58, 0, 0x10000
	v_add_u32_e32 v136, s58, v1
	s_add_i32 s60, 0, 0x14000
	ds_read_b128 v[150:153], v7
	ds_read_b128 v[154:157], v7 offset:1024
	ds_read_b128 v[158:161], v7 offset:2048
	ds_read_b128 v[162:165], v7 offset:3072
	ds_read_b128 v[166:169], v7 offset:4096
	ds_read_b128 v[170:173], v7 offset:5120
	ds_read_b128 v[174:177], v7 offset:6144
	ds_read_b128 v[178:181], v7 offset:7168
	ds_read_b128 v[182:185], v136
	ds_read_b128 v[186:189], v136 offset:1024
	ds_read_b128 v[190:193], v136 offset:2048
	ds_read_b128 v[194:197], v136 offset:3072
	v_add_u32_e32 v136, s60, v1
	ds_read_b128 v[208:211], v136
	ds_read_b128 v[212:215], v136 offset:1024
	ds_read_b128 v[216:219], v136 offset:2048
	ds_read_b128 v[220:223], v136 offset:3072
	v_lshl_add_u64 v[136:137], s[42:43], 0, v[146:147]
	s_add_i32 m0, s38, 0xc000
	s_nop 0
	global_load_lds_dwordx4 v[136:137], off
	v_lshl_add_u64 v[136:137], s[42:43], 0, v[148:149]
	s_add_i32 m0, s38, 0xe000
	s_nop 0
	global_load_lds_dwordx4 v[136:137], off
	s_waitcnt vmcnt(8)
	s_waitcnt lgkmcnt(0)
	s_barrier
	s_setprio 1
	s_waitcnt lgkmcnt(0)
	v_mfma_f32_16x16x32_bf16 v[132:135], v[182:185], v[150:153], v[132:135]
	v_mfma_f32_16x16x32_bf16 v[132:135], v[186:189], v[154:157], v[132:135]
	v_mfma_f32_16x16x32_bf16 v[124:127], v[182:185], v[158:161], v[124:127]
	v_mfma_f32_16x16x32_bf16 v[124:127], v[186:189], v[162:165], v[124:127]
	v_mfma_f32_16x16x32_bf16 v[116:119], v[182:185], v[166:169], v[116:119]
	v_mfma_f32_16x16x32_bf16 v[116:119], v[186:189], v[170:173], v[116:119]
	v_mfma_f32_16x16x32_bf16 v[100:103], v[182:185], v[174:177], v[100:103]
	v_mfma_f32_16x16x32_bf16 v[100:103], v[186:189], v[178:181], v[100:103]
	v_mfma_f32_16x16x32_bf16 v[128:131], v[190:193], v[150:153], v[128:131]
	v_mfma_f32_16x16x32_bf16 v[128:131], v[194:197], v[154:157], v[128:131]
	v_mfma_f32_16x16x32_bf16 v[120:123], v[190:193], v[158:161], v[120:123]
	v_mfma_f32_16x16x32_bf16 v[120:123], v[194:197], v[162:165], v[120:123]
	v_mfma_f32_16x16x32_bf16 v[108:111], v[190:193], v[166:169], v[108:111]
	v_mfma_f32_16x16x32_bf16 v[108:111], v[194:197], v[170:173], v[108:111]
	v_mfma_f32_16x16x32_bf16 v[92:95], v[190:193], v[174:177], v[92:95]
	v_mfma_f32_16x16x32_bf16 v[92:95], v[194:197], v[178:181], v[92:95]
	s_setprio 0
	s_setprio 1
	v_mfma_f32_16x16x32_bf16 v[112:115], v[208:211], v[150:153], v[112:115]
	v_mfma_f32_16x16x32_bf16 v[112:115], v[212:215], v[154:157], v[112:115]
	v_mfma_f32_16x16x32_bf16 v[96:99], v[208:211], v[158:161], v[96:99]
	v_mfma_f32_16x16x32_bf16 v[96:99], v[212:215], v[162:165], v[96:99]
	v_mfma_f32_16x16x32_bf16 v[84:87], v[208:211], v[166:169], v[84:87]
	v_mfma_f32_16x16x32_bf16 v[84:87], v[212:215], v[170:173], v[84:87]
	v_mfma_f32_16x16x32_bf16 v[76:79], v[208:211], v[174:177], v[76:79]
	v_mfma_f32_16x16x32_bf16 v[76:79], v[212:215], v[178:181], v[76:79]
	v_mfma_f32_16x16x32_bf16 v[104:107], v[216:219], v[150:153], v[104:107]
	v_mfma_f32_16x16x32_bf16 v[104:107], v[220:223], v[154:157], v[104:107]
	v_mfma_f32_16x16x32_bf16 v[88:91], v[216:219], v[158:161], v[88:91]
	v_mfma_f32_16x16x32_bf16 v[88:91], v[220:223], v[162:165], v[88:91]
	v_mfma_f32_16x16x32_bf16 v[80:83], v[216:219], v[166:169], v[80:83]
	v_mfma_f32_16x16x32_bf16 v[80:83], v[220:223], v[170:173], v[80:83]
	v_mfma_f32_16x16x32_bf16 v[72:75], v[216:219], v[174:177], v[72:75]
	v_mfma_f32_16x16x32_bf16 v[72:75], v[220:223], v[178:181], v[72:75]
	s_setprio 0
	s_barrier
	s_add_i32 s58, s58, s35
	v_lshl_add_u64 v[136:137], s[12:13], 0, v[2:3]
	s_mov_b32 m0, s58
	ds_read_b128 v[150:153], v7 offset:16384
	ds_read_b128 v[154:157], v7 offset:17408
	ds_read_b128 v[158:161], v7 offset:18432
	ds_read_b128 v[162:165], v7 offset:19456
	ds_read_b128 v[166:169], v7 offset:20480
	ds_read_b128 v[170:173], v7 offset:21504
	ds_read_b128 v[174:177], v7 offset:22528
	ds_read_b128 v[178:181], v7 offset:23552
	global_load_lds_dwordx4 v[136:137], off
	s_add_i32 m0, s58, 0x2000
	s_add_u32 s58, s12, 0x20000
	v_lshl_add_u64 v[198:199], s[12:13], 0, v[4:5]
	s_addc_u32 s59, s13, 0
	s_add_i32 s60, s60, s35
	global_load_lds_dwordx4 v[198:199], off
	v_lshl_add_u64 v[204:205], s[58:59], 0, v[2:3]
	s_mov_b32 m0, s60
	v_lshl_add_u64 v[224:225], s[14:15], 0, v[138:139]
	global_load_lds_dwordx4 v[204:205], off
	v_lshl_add_u64 v[204:205], s[58:59], 0, v[4:5]
	s_add_i32 m0, s60, 0x2000
	s_nop 0
	global_load_lds_dwordx4 v[204:205], off
	v_lshl_add_u64 v[204:205], s[14:15], 0, v[140:141]
	s_mov_b32 m0, s38
	s_nop 0
	global_load_lds_dwordx4 v[204:205], off
	s_mov_b32 m0, s39
	s_nop 0
	global_load_lds_dwordx4 v[224:225], off
	s_waitcnt vmcnt(8)
	s_waitcnt lgkmcnt(0)
	s_barrier
	s_setprio 1
	s_waitcnt lgkmcnt(0)
	v_mfma_f32_16x16x32_bf16 v[68:71], v[182:185], v[150:153], v[68:71]
	v_mfma_f32_16x16x32_bf16 v[68:71], v[186:189], v[154:157], v[68:71]
	v_mfma_f32_16x16x32_bf16 v[60:63], v[182:185], v[158:161], v[60:63]
	v_mfma_f32_16x16x32_bf16 v[60:63], v[186:189], v[162:165], v[60:63]
	v_mfma_f32_16x16x32_bf16 v[52:55], v[182:185], v[166:169], v[52:55]
	v_mfma_f32_16x16x32_bf16 v[52:55], v[186:189], v[170:173], v[52:55]
	v_mfma_f32_16x16x32_bf16 v[36:39], v[182:185], v[174:177], v[36:39]
	v_mfma_f32_16x16x32_bf16 v[36:39], v[186:189], v[178:181], v[36:39]
	v_mfma_f32_16x16x32_bf16 v[64:67], v[190:193], v[150:153], v[64:67]
	v_mfma_f32_16x16x32_bf16 v[64:67], v[194:197], v[154:157], v[64:67]
	v_mfma_f32_16x16x32_bf16 v[56:59], v[190:193], v[158:161], v[56:59]
	v_mfma_f32_16x16x32_bf16 v[56:59], v[194:197], v[162:165], v[56:59]
	v_mfma_f32_16x16x32_bf16 v[44:47], v[190:193], v[166:169], v[44:47]
	v_mfma_f32_16x16x32_bf16 v[44:47], v[194:197], v[170:173], v[44:47]
	v_mfma_f32_16x16x32_bf16 v[28:31], v[190:193], v[174:177], v[28:31]
	v_mfma_f32_16x16x32_bf16 v[28:31], v[194:197], v[178:181], v[28:31]
	s_setprio 0
	s_setprio 1
	v_mfma_f32_16x16x32_bf16 v[48:51], v[208:211], v[150:153], v[48:51]
	v_mfma_f32_16x16x32_bf16 v[48:51], v[212:215], v[154:157], v[48:51]
	v_mfma_f32_16x16x32_bf16 v[32:35], v[208:211], v[158:161], v[32:35]
	v_mfma_f32_16x16x32_bf16 v[32:35], v[212:215], v[162:165], v[32:35]
	v_mfma_f32_16x16x32_bf16 v[20:23], v[208:211], v[166:169], v[20:23]
	v_mfma_f32_16x16x32_bf16 v[20:23], v[212:215], v[170:173], v[20:23]
	v_mfma_f32_16x16x32_bf16 v[12:15], v[208:211], v[174:177], v[12:15]
	v_mfma_f32_16x16x32_bf16 v[12:15], v[212:215], v[178:181], v[12:15]
	v_mfma_f32_16x16x32_bf16 v[40:43], v[216:219], v[150:153], v[40:43]
	v_mfma_f32_16x16x32_bf16 v[40:43], v[220:223], v[154:157], v[40:43]
	v_mfma_f32_16x16x32_bf16 v[24:27], v[216:219], v[158:161], v[24:27]
	v_mfma_f32_16x16x32_bf16 v[24:27], v[220:223], v[162:165], v[24:27]
	v_mfma_f32_16x16x32_bf16 v[16:19], v[216:219], v[166:169], v[16:19]
	v_mfma_f32_16x16x32_bf16 v[16:19], v[220:223], v[170:173], v[16:19]
	v_mfma_f32_16x16x32_bf16 v[8:11], v[216:219], v[174:177], v[8:11]
	v_mfma_f32_16x16x32_bf16 v[8:11], v[220:223], v[178:181], v[8:11]
	s_setprio 0
	s_barrier
	s_add_i32 s58, 0, 0x18000
	s_add_i32 s59, 0, 0x1c000
	s_add_u32 s14, s14, 0x20000
	s_addc_u32 s15, s15, 0
	s_mov_b32 m0, s40
	v_add_u32_e32 v194, s58, v1
	v_add_u32_e32 v207, s59, v1
	v_lshl_add_u64 v[226:227], s[14:15], 0, v[140:141]
	ds_read_b128 v[150:153], v7 offset:32768
	ds_read_b128 v[154:157], v7 offset:33792
	ds_read_b128 v[158:161], v7 offset:34816
	ds_read_b128 v[162:165], v7 offset:35840
	ds_read_b128 v[166:169], v7 offset:36864
	ds_read_b128 v[170:173], v7 offset:37888
	ds_read_b128 v[174:177], v7 offset:38912
	ds_read_b128 v[178:181], v7 offset:39936
	ds_read_b128 v[182:185], v194
	ds_read_b128 v[186:189], v194 offset:1024
	ds_read_b128 v[190:193], v194 offset:2048
	ds_read_b128 v[194:197], v194 offset:3072
	ds_read_b128 v[208:211], v207
	ds_read_b128 v[212:215], v207 offset:1024
	ds_read_b128 v[216:219], v207 offset:2048
	ds_read_b128 v[220:223], v207 offset:3072
	global_load_lds_dwordx4 v[226:227], off
	v_lshl_add_u64 v[226:227], s[14:15], 0, v[138:139]
	s_mov_b32 m0, s41
	s_nop 0
	global_load_lds_dwordx4 v[226:227], off
	s_waitcnt vmcnt(8)
	s_waitcnt lgkmcnt(0)
	s_barrier
	s_setprio 1
	s_waitcnt lgkmcnt(0)
	v_mfma_f32_16x16x32_bf16 v[132:135], v[182:185], v[150:153], v[132:135]
	v_mfma_f32_16x16x32_bf16 v[132:135], v[186:189], v[154:157], v[132:135]
	v_mfma_f32_16x16x32_bf16 v[124:127], v[182:185], v[158:161], v[124:127]
	v_mfma_f32_16x16x32_bf16 v[124:127], v[186:189], v[162:165], v[124:127]
	v_mfma_f32_16x16x32_bf16 v[116:119], v[182:185], v[166:169], v[116:119]
	v_mfma_f32_16x16x32_bf16 v[116:119], v[186:189], v[170:173], v[116:119]
	v_mfma_f32_16x16x32_bf16 v[100:103], v[182:185], v[174:177], v[100:103]
	v_mfma_f32_16x16x32_bf16 v[100:103], v[186:189], v[178:181], v[100:103]
	v_mfma_f32_16x16x32_bf16 v[128:131], v[190:193], v[150:153], v[128:131]
	v_mfma_f32_16x16x32_bf16 v[128:131], v[194:197], v[154:157], v[128:131]
	v_mfma_f32_16x16x32_bf16 v[120:123], v[190:193], v[158:161], v[120:123]
	v_mfma_f32_16x16x32_bf16 v[120:123], v[194:197], v[162:165], v[120:123]
	v_mfma_f32_16x16x32_bf16 v[108:111], v[190:193], v[166:169], v[108:111]
	v_mfma_f32_16x16x32_bf16 v[108:111], v[194:197], v[170:173], v[108:111]
	v_mfma_f32_16x16x32_bf16 v[92:95], v[190:193], v[174:177], v[92:95]
	v_mfma_f32_16x16x32_bf16 v[92:95], v[194:197], v[178:181], v[92:95]
	s_setprio 0
	s_setprio 1
	v_mfma_f32_16x16x32_bf16 v[112:115], v[208:211], v[150:153], v[112:115]
	v_mfma_f32_16x16x32_bf16 v[112:115], v[212:215], v[154:157], v[112:115]
	v_mfma_f32_16x16x32_bf16 v[96:99], v[208:211], v[158:161], v[96:99]
	v_mfma_f32_16x16x32_bf16 v[96:99], v[212:215], v[162:165], v[96:99]
	v_mfma_f32_16x16x32_bf16 v[84:87], v[208:211], v[166:169], v[84:87]
	v_mfma_f32_16x16x32_bf16 v[84:87], v[212:215], v[170:173], v[84:87]
	v_mfma_f32_16x16x32_bf16 v[76:79], v[208:211], v[174:177], v[76:79]
	v_mfma_f32_16x16x32_bf16 v[76:79], v[212:215], v[178:181], v[76:79]
	v_mfma_f32_16x16x32_bf16 v[104:107], v[216:219], v[150:153], v[104:107]
	v_mfma_f32_16x16x32_bf16 v[104:107], v[220:223], v[154:157], v[104:107]
	v_mfma_f32_16x16x32_bf16 v[88:91], v[216:219], v[158:161], v[88:91]
	v_mfma_f32_16x16x32_bf16 v[88:91], v[220:223], v[162:165], v[88:91]
	v_mfma_f32_16x16x32_bf16 v[80:83], v[216:219], v[166:169], v[80:83]
	v_mfma_f32_16x16x32_bf16 v[80:83], v[220:223], v[170:173], v[80:83]
	v_mfma_f32_16x16x32_bf16 v[72:75], v[216:219], v[174:177], v[72:75]
	v_mfma_f32_16x16x32_bf16 v[72:75], v[220:223], v[178:181], v[72:75]
	s_setprio 0
	s_barrier
	s_add_i32 s14, s58, s35
	v_lshl_add_u64 v[136:137], v[136:137], 0, s[0:1]
	s_mov_b32 m0, s14
	ds_read_b128 v[150:153], v7 offset:49152
	ds_read_b128 v[154:157], v7 offset:50176
	ds_read_b128 v[158:161], v7 offset:51200
	ds_read_b128 v[162:165], v7 offset:52224
	ds_read_b128 v[166:169], v7 offset:53248
	ds_read_b128 v[170:173], v7 offset:54272
	ds_read_b128 v[174:177], v7 offset:55296
	ds_read_b128 v[178:181], v7 offset:56320
	global_load_lds_dwordx4 v[136:137], off
	s_add_i32 m0, s14, 0x2000
	s_add_u32 s12, s12, 0x20080
	v_lshl_add_u64 v[136:137], v[198:199], 0, s[0:1]
	s_addc_u32 s13, s13, 0
	s_add_i32 s14, s59, s35
	global_load_lds_dwordx4 v[136:137], off
	v_lshl_add_u64 v[136:137], s[12:13], 0, v[2:3]
	s_mov_b32 m0, s14
	s_nop 0
	global_load_lds_dwordx4 v[136:137], off
	v_lshl_add_u64 v[136:137], s[12:13], 0, v[4:5]
	s_add_i32 m0, s14, 0x2000
	s_nop 0
	global_load_lds_dwordx4 v[136:137], off
	v_lshl_add_u64 v[136:137], v[204:205], 0, s[0:1]
	s_mov_b32 m0, s49
	s_nop 0
	global_load_lds_dwordx4 v[136:137], off
	v_lshl_add_u64 v[136:137], v[224:225], 0, s[0:1]
	s_mov_b32 m0, s52
	s_nop 0
	global_load_lds_dwordx4 v[136:137], off
	s_waitcnt vmcnt(8)
	s_waitcnt lgkmcnt(0)
	s_barrier
	s_setprio 1
	s_waitcnt lgkmcnt(0)
	v_mfma_f32_16x16x32_bf16 v[68:71], v[182:185], v[150:153], v[68:71]
	v_mfma_f32_16x16x32_bf16 v[68:71], v[186:189], v[154:157], v[68:71]
	v_mfma_f32_16x16x32_bf16 v[60:63], v[182:185], v[158:161], v[60:63]
	v_mfma_f32_16x16x32_bf16 v[60:63], v[186:189], v[162:165], v[60:63]
	v_mfma_f32_16x16x32_bf16 v[52:55], v[182:185], v[166:169], v[52:55]
	v_mfma_f32_16x16x32_bf16 v[52:55], v[186:189], v[170:173], v[52:55]
	v_mfma_f32_16x16x32_bf16 v[36:39], v[182:185], v[174:177], v[36:39]
	v_mfma_f32_16x16x32_bf16 v[36:39], v[186:189], v[178:181], v[36:39]
	v_mfma_f32_16x16x32_bf16 v[64:67], v[190:193], v[150:153], v[64:67]
	v_mfma_f32_16x16x32_bf16 v[64:67], v[194:197], v[154:157], v[64:67]
	v_mfma_f32_16x16x32_bf16 v[56:59], v[190:193], v[158:161], v[56:59]
	v_mfma_f32_16x16x32_bf16 v[56:59], v[194:197], v[162:165], v[56:59]
	v_mfma_f32_16x16x32_bf16 v[44:47], v[190:193], v[166:169], v[44:47]
	v_mfma_f32_16x16x32_bf16 v[44:47], v[194:197], v[170:173], v[44:47]
	v_mfma_f32_16x16x32_bf16 v[28:31], v[190:193], v[174:177], v[28:31]
	v_mfma_f32_16x16x32_bf16 v[28:31], v[194:197], v[178:181], v[28:31]
	s_setprio 0
	s_setprio 1
	v_mfma_f32_16x16x32_bf16 v[48:51], v[208:211], v[150:153], v[48:51]
	v_mfma_f32_16x16x32_bf16 v[48:51], v[212:215], v[154:157], v[48:51]
	v_mfma_f32_16x16x32_bf16 v[32:35], v[208:211], v[158:161], v[32:35]
	v_mfma_f32_16x16x32_bf16 v[32:35], v[212:215], v[162:165], v[32:35]
	v_mfma_f32_16x16x32_bf16 v[20:23], v[208:211], v[166:169], v[20:23]
	v_mfma_f32_16x16x32_bf16 v[20:23], v[212:215], v[170:173], v[20:23]
	v_mfma_f32_16x16x32_bf16 v[12:15], v[208:211], v[174:177], v[12:15]
	v_mfma_f32_16x16x32_bf16 v[12:15], v[212:215], v[178:181], v[12:15]
	v_mfma_f32_16x16x32_bf16 v[40:43], v[216:219], v[150:153], v[40:43]
	v_mfma_f32_16x16x32_bf16 v[40:43], v[220:223], v[154:157], v[40:43]
	v_mfma_f32_16x16x32_bf16 v[24:27], v[216:219], v[158:161], v[24:27]
	v_mfma_f32_16x16x32_bf16 v[24:27], v[220:223], v[162:165], v[24:27]
	v_mfma_f32_16x16x32_bf16 v[16:19], v[216:219], v[166:169], v[16:19]
	v_mfma_f32_16x16x32_bf16 v[16:19], v[220:223], v[170:173], v[16:19]
	v_mfma_f32_16x16x32_bf16 v[8:11], v[216:219], v[174:177], v[8:11]
	v_mfma_f32_16x16x32_bf16 v[8:11], v[220:223], v[178:181], v[8:11]
	s_setprio 0
	s_barrier
	s_add_i32 s57, s57, 2
	s_add_u32 s42, s42, 0x100
	s_addc_u32 s43, s43, 0
	s_add_u32 s26, s26, 0x100
	s_addc_u32 s27, s27, 0
	s_cmp_gt_u32 s57, 5
	s_cbranch_scc0 .LBB0_620
	s_and_b64 vcc, exec, s[6:7]
	s_cbranch_vccz .LBB0_623
	s_barrier

.LBB0_986:
	s_add_u32 s12, s44, 0xfff80080
	s_addc_u32 s13, s45, -1
	s_cmp_eq_u32 s50, 28
	s_cselect_b32 s15, s18, s13
	s_cselect_b32 s14, s19, s12
	s_cselect_b32 s13, s17, s43
	s_cselect_b32 s12, s21, s33
	s_add_i32 s51, 0, 0x10000
	v_add_u32_e32 v2, s51, v7
	s_add_i32 s63, 0, 0x14000
	ds_read_b128 v[150:153], v155
	ds_read_b128 v[156:159], v155 offset:1024
	ds_read_b128 v[160:163], v155 offset:2048
	ds_read_b128 v[164:167], v155 offset:3072
	ds_read_b128 v[168:171], v155 offset:4096
	ds_read_b128 v[172:175], v155 offset:5120
	ds_read_b128 v[176:179], v155 offset:6144
	ds_read_b128 v[180:183], v155 offset:7168
	ds_read_b128 v[184:187], v2
	ds_read_b128 v[188:191], v2 offset:1024
	ds_read_b128 v[192:195], v2 offset:2048
	ds_read_b128 v[196:199], v2 offset:3072
	v_add_u32_e32 v2, s63, v7
	v_lshl_add_u64 v[224:225], s[44:45], 0, v[146:147]
	s_add_i32 m0, s39, 0xc000
	ds_read_b128 v[208:211], v2
	ds_read_b128 v[212:215], v2 offset:1024
	ds_read_b128 v[216:219], v2 offset:2048
	ds_read_b128 v[220:223], v2 offset:3072
	global_load_lds_dwordx4 v[224:225], off
	v_lshl_add_u64 v[224:225], s[44:45], 0, v[148:149]
	s_add_i32 m0, s39, 0xe000
	s_nop 0
	global_load_lds_dwordx4 v[224:225], off
	s_waitcnt vmcnt(8)
	s_waitcnt lgkmcnt(0)
	s_barrier
	s_setprio 1
	s_waitcnt lgkmcnt(0)
	v_mfma_f32_16x16x32_bf16 v[132:135], v[184:187], v[150:153], v[132:135]
	v_mfma_f32_16x16x32_bf16 v[132:135], v[188:191], v[156:159], v[132:135]
	v_mfma_f32_16x16x32_bf16 v[116:119], v[184:187], v[160:163], v[116:119]
	v_mfma_f32_16x16x32_bf16 v[116:119], v[188:191], v[164:167], v[116:119]
	v_mfma_f32_16x16x32_bf16 v[100:103], v[184:187], v[168:171], v[100:103]
	v_mfma_f32_16x16x32_bf16 v[100:103], v[188:191], v[172:175], v[100:103]
	v_mfma_f32_16x16x32_bf16 v[84:87], v[184:187], v[176:179], v[84:87]
	v_mfma_f32_16x16x32_bf16 v[84:87], v[188:191], v[180:183], v[84:87]
	v_mfma_f32_16x16x32_bf16 v[128:131], v[192:195], v[150:153], v[128:131]
	v_mfma_f32_16x16x32_bf16 v[128:131], v[196:199], v[156:159], v[128:131]
	v_mfma_f32_16x16x32_bf16 v[112:115], v[192:195], v[160:163], v[112:115]
	v_mfma_f32_16x16x32_bf16 v[112:115], v[196:199], v[164:167], v[112:115]
	v_mfma_f32_16x16x32_bf16 v[96:99], v[192:195], v[168:171], v[96:99]
	v_mfma_f32_16x16x32_bf16 v[96:99], v[196:199], v[172:175], v[96:99]
	v_mfma_f32_16x16x32_bf16 v[80:83], v[192:195], v[176:179], v[80:83]
	v_mfma_f32_16x16x32_bf16 v[80:83], v[196:199], v[180:183], v[80:83]
	s_setprio 0
	s_setprio 1
	v_mfma_f32_16x16x32_bf16 v[124:127], v[208:211], v[150:153], v[124:127]
	v_mfma_f32_16x16x32_bf16 v[124:127], v[212:215], v[156:159], v[124:127]
	v_mfma_f32_16x16x32_bf16 v[108:111], v[208:211], v[160:163], v[108:111]
	v_mfma_f32_16x16x32_bf16 v[108:111], v[212:215], v[164:167], v[108:111]
	v_mfma_f32_16x16x32_bf16 v[92:95], v[208:211], v[168:171], v[92:95]
	v_mfma_f32_16x16x32_bf16 v[92:95], v[212:215], v[172:175], v[92:95]
	v_mfma_f32_16x16x32_bf16 v[76:79], v[208:211], v[176:179], v[76:79]
	v_mfma_f32_16x16x32_bf16 v[76:79], v[212:215], v[180:183], v[76:79]
	v_mfma_f32_16x16x32_bf16 v[120:123], v[216:219], v[150:153], v[120:123]
	v_mfma_f32_16x16x32_bf16 v[120:123], v[220:223], v[156:159], v[120:123]
	v_mfma_f32_16x16x32_bf16 v[104:107], v[216:219], v[160:163], v[104:107]
	v_mfma_f32_16x16x32_bf16 v[104:107], v[220:223], v[164:167], v[104:107]
	v_mfma_f32_16x16x32_bf16 v[88:91], v[216:219], v[168:171], v[88:91]
	v_mfma_f32_16x16x32_bf16 v[88:91], v[220:223], v[172:175], v[88:91]
	v_mfma_f32_16x16x32_bf16 v[72:75], v[216:219], v[176:179], v[72:75]
	v_mfma_f32_16x16x32_bf16 v[72:75], v[220:223], v[180:183], v[72:75]
	s_setprio 0
	s_barrier
	s_add_i32 s51, s51, s38
	v_lshl_add_u64 v[224:225], s[12:13], 0, v[138:139]
	s_mov_b32 m0, s51
	ds_read_b128 v[150:153], v155 offset:16384
	ds_read_b128 v[156:159], v155 offset:17408
	ds_read_b128 v[160:163], v155 offset:18432
	ds_read_b128 v[164:167], v155 offset:19456
	ds_read_b128 v[168:171], v155 offset:20480
	ds_read_b128 v[172:175], v155 offset:21504
	ds_read_b128 v[176:179], v155 offset:22528
	ds_read_b128 v[180:183], v155 offset:23552
	global_load_lds_dwordx4 v[224:225], off
	s_add_i32 m0, s51, 0x2000
	s_add_u32 s64, s12, 0x80000
	v_lshl_add_u64 v[226:227], s[12:13], 0, v[4:5]
	s_addc_u32 s65, s13, 0
	s_add_i32 s51, s63, s38
	global_load_lds_dwordx4 v[226:227], off
	v_lshl_add_u64 v[228:229], s[64:65], 0, v[138:139]
	s_mov_b32 m0, s51
	v_lshl_add_u64 v[230:231], s[14:15], 0, v[136:137]
	global_load_lds_dwordx4 v[228:229], off
	v_lshl_add_u64 v[228:229], s[64:65], 0, v[4:5]
	s_add_i32 m0, s51, 0x2000
	s_nop 0
	global_load_lds_dwordx4 v[228:229], off
	v_lshl_add_u64 v[228:229], s[14:15], 0, v[140:141]
	s_mov_b32 m0, s39
	s_nop 0
	global_load_lds_dwordx4 v[228:229], off
	s_mov_b32 m0, s40
	s_nop 0
	global_load_lds_dwordx4 v[230:231], off
	s_waitcnt vmcnt(8)
	s_waitcnt lgkmcnt(0)
	s_barrier
	s_setprio 1
	s_waitcnt lgkmcnt(0)
	v_mfma_f32_16x16x32_bf16 v[68:71], v[184:187], v[150:153], v[68:71]
	v_mfma_f32_16x16x32_bf16 v[68:71], v[188:191], v[156:159], v[68:71]
	v_mfma_f32_16x16x32_bf16 v[52:55], v[184:187], v[160:163], v[52:55]
	v_mfma_f32_16x16x32_bf16 v[52:55], v[188:191], v[164:167], v[52:55]
	v_mfma_f32_16x16x32_bf16 v[36:39], v[184:187], v[168:171], v[36:39]
	v_mfma_f32_16x16x32_bf16 v[36:39], v[188:191], v[172:175], v[36:39]
	v_mfma_f32_16x16x32_bf16 v[20:23], v[184:187], v[176:179], v[20:23]
	v_mfma_f32_16x16x32_bf16 v[20:23], v[188:191], v[180:183], v[20:23]
	v_mfma_f32_16x16x32_bf16 v[64:67], v[192:195], v[150:153], v[64:67]
	v_mfma_f32_16x16x32_bf16 v[64:67], v[196:199], v[156:159], v[64:67]
	v_mfma_f32_16x16x32_bf16 v[48:51], v[192:195], v[160:163], v[48:51]
	v_mfma_f32_16x16x32_bf16 v[48:51], v[196:199], v[164:167], v[48:51]
	v_mfma_f32_16x16x32_bf16 v[32:35], v[192:195], v[168:171], v[32:35]
	v_mfma_f32_16x16x32_bf16 v[32:35], v[196:199], v[172:175], v[32:35]
	v_mfma_f32_16x16x32_bf16 v[16:19], v[192:195], v[176:179], v[16:19]
	v_mfma_f32_16x16x32_bf16 v[16:19], v[196:199], v[180:183], v[16:19]
	s_setprio 0
	s_setprio 1
	v_mfma_f32_16x16x32_bf16 v[60:63], v[208:211], v[150:153], v[60:63]
	v_mfma_f32_16x16x32_bf16 v[60:63], v[212:215], v[156:159], v[60:63]
	v_mfma_f32_16x16x32_bf16 v[44:47], v[208:211], v[160:163], v[44:47]
	v_mfma_f32_16x16x32_bf16 v[44:47], v[212:215], v[164:167], v[44:47]
	v_mfma_f32_16x16x32_bf16 v[28:31], v[208:211], v[168:171], v[28:31]
	v_mfma_f32_16x16x32_bf16 v[28:31], v[212:215], v[172:175], v[28:31]
	v_mfma_f32_16x16x32_bf16 v[12:15], v[208:211], v[176:179], v[12:15]
	v_mfma_f32_16x16x32_bf16 v[12:15], v[212:215], v[180:183], v[12:15]
	v_mfma_f32_16x16x32_bf16 v[56:59], v[216:219], v[150:153], v[56:59]
	v_mfma_f32_16x16x32_bf16 v[56:59], v[220:223], v[156:159], v[56:59]
	v_mfma_f32_16x16x32_bf16 v[40:43], v[216:219], v[160:163], v[40:43]
	v_mfma_f32_16x16x32_bf16 v[40:43], v[220:223], v[164:167], v[40:43]
	v_mfma_f32_16x16x32_bf16 v[24:27], v[216:219], v[168:171], v[24:27]
	v_mfma_f32_16x16x32_bf16 v[24:27], v[220:223], v[172:175], v[24:27]
	v_mfma_f32_16x16x32_bf16 v[8:11], v[216:219], v[176:179], v[8:11]
	v_mfma_f32_16x16x32_bf16 v[8:11], v[220:223], v[180:183], v[8:11]
	s_setprio 0
	s_barrier
	s_add_i32 s51, 0, 0x18000
	s_add_i32 s63, 0, 0x1c000
	s_add_u32 s14, s14, 0x80000
	v_add_u32_e32 v2, s51, v7
	s_addc_u32 s15, s15, 0
	s_mov_b32 m0, s41
	ds_read_b128 v[150:153], v155 offset:32768
	ds_read_b128 v[156:159], v155 offset:33792
	ds_read_b128 v[160:163], v155 offset:34816
	ds_read_b128 v[164:167], v155 offset:35840
	ds_read_b128 v[168:171], v155 offset:36864
	ds_read_b128 v[172:175], v155 offset:37888
	ds_read_b128 v[176:179], v155 offset:38912
	ds_read_b128 v[180:183], v155 offset:39936
	ds_read_b128 v[184:187], v2
	ds_read_b128 v[188:191], v2 offset:1024
	ds_read_b128 v[192:195], v2 offset:2048
	ds_read_b128 v[196:199], v2 offset:3072
	v_add_u32_e32 v2, s63, v7
	v_lshl_add_u64 v[232:233], s[14:15], 0, v[140:141]
	ds_read_b128 v[208:211], v2
	ds_read_b128 v[212:215], v2 offset:1024
	ds_read_b128 v[216:219], v2 offset:2048
	ds_read_b128 v[220:223], v2 offset:3072
	global_load_lds_dwordx4 v[232:233], off
	v_lshl_add_u64 v[232:233], s[14:15], 0, v[136:137]
	s_mov_b32 m0, s47
	s_nop 0
	global_load_lds_dwordx4 v[232:233], off
	s_waitcnt vmcnt(8)
	s_waitcnt lgkmcnt(0)
	s_barrier
	s_setprio 1
	s_waitcnt lgkmcnt(0)
	v_mfma_f32_16x16x32_bf16 v[132:135], v[184:187], v[150:153], v[132:135]
	v_mfma_f32_16x16x32_bf16 v[132:135], v[188:191], v[156:159], v[132:135]
	v_mfma_f32_16x16x32_bf16 v[116:119], v[184:187], v[160:163], v[116:119]
	v_mfma_f32_16x16x32_bf16 v[116:119], v[188:191], v[164:167], v[116:119]
	v_mfma_f32_16x16x32_bf16 v[100:103], v[184:187], v[168:171], v[100:103]
	v_mfma_f32_16x16x32_bf16 v[100:103], v[188:191], v[172:175], v[100:103]
	v_mfma_f32_16x16x32_bf16 v[84:87], v[184:187], v[176:179], v[84:87]
	v_mfma_f32_16x16x32_bf16 v[84:87], v[188:191], v[180:183], v[84:87]
	v_mfma_f32_16x16x32_bf16 v[128:131], v[192:195], v[150:153], v[128:131]
	v_mfma_f32_16x16x32_bf16 v[128:131], v[196:199], v[156:159], v[128:131]
	v_mfma_f32_16x16x32_bf16 v[112:115], v[192:195], v[160:163], v[112:115]
	v_mfma_f32_16x16x32_bf16 v[112:115], v[196:199], v[164:167], v[112:115]
	v_mfma_f32_16x16x32_bf16 v[96:99], v[192:195], v[168:171], v[96:99]
	v_mfma_f32_16x16x32_bf16 v[96:99], v[196:199], v[172:175], v[96:99]
	v_mfma_f32_16x16x32_bf16 v[80:83], v[192:195], v[176:179], v[80:83]
	v_mfma_f32_16x16x32_bf16 v[80:83], v[196:199], v[180:183], v[80:83]
	s_setprio 0
	s_setprio 1
	v_mfma_f32_16x16x32_bf16 v[124:127], v[208:211], v[150:153], v[124:127]
	v_mfma_f32_16x16x32_bf16 v[124:127], v[212:215], v[156:159], v[124:127]
	v_mfma_f32_16x16x32_bf16 v[108:111], v[208:211], v[160:163], v[108:111]
	v_mfma_f32_16x16x32_bf16 v[108:111], v[212:215], v[164:167], v[108:111]
	v_mfma_f32_16x16x32_bf16 v[92:95], v[208:211], v[168:171], v[92:95]
	v_mfma_f32_16x16x32_bf16 v[92:95], v[212:215], v[172:175], v[92:95]
	v_mfma_f32_16x16x32_bf16 v[76:79], v[208:211], v[176:179], v[76:79]
	v_mfma_f32_16x16x32_bf16 v[76:79], v[212:215], v[180:183], v[76:79]
	v_mfma_f32_16x16x32_bf16 v[120:123], v[216:219], v[150:153], v[120:123]
	v_mfma_f32_16x16x32_bf16 v[120:123], v[220:223], v[156:159], v[120:123]
	v_mfma_f32_16x16x32_bf16 v[104:107], v[216:219], v[160:163], v[104:107]
	v_mfma_f32_16x16x32_bf16 v[104:107], v[220:223], v[164:167], v[104:107]
	v_mfma_f32_16x16x32_bf16 v[88:91], v[216:219], v[168:171], v[88:91]
	v_mfma_f32_16x16x32_bf16 v[88:91], v[220:223], v[172:175], v[88:91]
	v_mfma_f32_16x16x32_bf16 v[72:75], v[216:219], v[176:179], v[72:75]
	v_mfma_f32_16x16x32_bf16 v[72:75], v[220:223], v[180:183], v[72:75]
	s_setprio 0
	s_barrier
	s_add_i32 s14, s51, s38
	v_lshl_add_u64 v[224:225], v[224:225], 0, s[0:1]
	s_mov_b32 m0, s14
	ds_read_b128 v[150:153], v155 offset:49152
	ds_read_b128 v[156:159], v155 offset:50176
	ds_read_b128 v[160:163], v155 offset:51200
	ds_read_b128 v[164:167], v155 offset:52224
	ds_read_b128 v[168:171], v155 offset:53248
	ds_read_b128 v[172:175], v155 offset:54272
	ds_read_b128 v[176:179], v155 offset:55296
	ds_read_b128 v[180:183], v155 offset:56320
	global_load_lds_dwordx4 v[224:225], off
	s_add_i32 m0, s14, 0x2000
	s_add_u32 s12, s12, 0x80080
	v_lshl_add_u64 v[224:225], v[226:227], 0, s[0:1]
	s_addc_u32 s13, s13, 0
	s_add_i32 s14, s63, s38
	global_load_lds_dwordx4 v[224:225], off
	v_lshl_add_u64 v[224:225], s[12:13], 0, v[138:139]
	s_mov_b32 m0, s14
	s_nop 0
	global_load_lds_dwordx4 v[224:225], off
	v_lshl_add_u64 v[224:225], s[12:13], 0, v[4:5]
	s_add_i32 m0, s14, 0x2000
	s_nop 0
	global_load_lds_dwordx4 v[224:225], off
	v_lshl_add_u64 v[224:225], v[228:229], 0, s[0:1]
	s_mov_b32 m0, s60
	s_nop 0
	global_load_lds_dwordx4 v[224:225], off
	v_lshl_add_u64 v[224:225], v[230:231], 0, s[0:1]
	s_mov_b32 m0, s61
	s_nop 0
	global_load_lds_dwordx4 v[224:225], off
	s_waitcnt vmcnt(8)
	s_waitcnt lgkmcnt(0)
	s_barrier
	s_setprio 1
	s_waitcnt lgkmcnt(0)
	v_mfma_f32_16x16x32_bf16 v[68:71], v[184:187], v[150:153], v[68:71]
	v_mfma_f32_16x16x32_bf16 v[68:71], v[188:191], v[156:159], v[68:71]
	v_mfma_f32_16x16x32_bf16 v[52:55], v[184:187], v[160:163], v[52:55]
	v_mfma_f32_16x16x32_bf16 v[52:55], v[188:191], v[164:167], v[52:55]
	v_mfma_f32_16x16x32_bf16 v[36:39], v[184:187], v[168:171], v[36:39]
	v_mfma_f32_16x16x32_bf16 v[36:39], v[188:191], v[172:175], v[36:39]
	v_mfma_f32_16x16x32_bf16 v[20:23], v[184:187], v[176:179], v[20:23]
	v_mfma_f32_16x16x32_bf16 v[20:23], v[188:191], v[180:183], v[20:23]
	v_mfma_f32_16x16x32_bf16 v[64:67], v[192:195], v[150:153], v[64:67]
	v_mfma_f32_16x16x32_bf16 v[64:67], v[196:199], v[156:159], v[64:67]
	v_mfma_f32_16x16x32_bf16 v[48:51], v[192:195], v[160:163], v[48:51]
	v_mfma_f32_16x16x32_bf16 v[48:51], v[196:199], v[164:167], v[48:51]
	v_mfma_f32_16x16x32_bf16 v[32:35], v[192:195], v[168:171], v[32:35]
	v_mfma_f32_16x16x32_bf16 v[32:35], v[196:199], v[172:175], v[32:35]
	v_mfma_f32_16x16x32_bf16 v[16:19], v[192:195], v[176:179], v[16:19]
	v_mfma_f32_16x16x32_bf16 v[16:19], v[196:199], v[180:183], v[16:19]
	s_setprio 0
	s_setprio 1
	v_mfma_f32_16x16x32_bf16 v[60:63], v[208:211], v[150:153], v[60:63]
	v_mfma_f32_16x16x32_bf16 v[60:63], v[212:215], v[156:159], v[60:63]
	v_mfma_f32_16x16x32_bf16 v[44:47], v[208:211], v[160:163], v[44:47]
	v_mfma_f32_16x16x32_bf16 v[44:47], v[212:215], v[164:167], v[44:47]
	v_mfma_f32_16x16x32_bf16 v[28:31], v[208:211], v[168:171], v[28:31]
	v_mfma_f32_16x16x32_bf16 v[28:31], v[212:215], v[172:175], v[28:31]
	v_mfma_f32_16x16x32_bf16 v[12:15], v[208:211], v[176:179], v[12:15]
	v_mfma_f32_16x16x32_bf16 v[12:15], v[212:215], v[180:183], v[12:15]
	v_mfma_f32_16x16x32_bf16 v[56:59], v[216:219], v[150:153], v[56:59]
	v_mfma_f32_16x16x32_bf16 v[56:59], v[220:223], v[156:159], v[56:59]
	v_mfma_f32_16x16x32_bf16 v[40:43], v[216:219], v[160:163], v[40:43]
	v_mfma_f32_16x16x32_bf16 v[40:43], v[220:223], v[164:167], v[40:43]
	v_mfma_f32_16x16x32_bf16 v[24:27], v[216:219], v[168:171], v[24:27]
	v_mfma_f32_16x16x32_bf16 v[24:27], v[220:223], v[172:175], v[24:27]
	v_mfma_f32_16x16x32_bf16 v[8:11], v[216:219], v[176:179], v[8:11]
	v_mfma_f32_16x16x32_bf16 v[8:11], v[220:223], v[180:183], v[8:11]
	s_setprio 0
	s_barrier
	s_add_i32 s50, s50, 2
	s_add_u32 s44, s44, 0x100
	s_addc_u32 s45, s45, 0
	s_add_u32 s33, s33, 0x100
	s_addc_u32 s43, s43, 0
	s_cmp_gt_u32 s50, 29
	s_cbranch_scc0 .LBB0_986
	s_and_b64 vcc, exec, s[10:11]
	s_cbranch_vccz .LBB0_1031
	s_barrier
	s_cmp_gt_i32 s35, 15
	s_mov_b64 s[12:13], -1
	s_cbranch_scc1 .LBB0_1032

.LBB0_1482:
	s_add_i32 s26, s12, 2
	s_cmp_eq_u32 s57, s12
	s_cselect_b32 s13, s43, s51
	s_cselect_b32 s12, s42, s50
	s_cselect_b32 s65, s45, s15
	s_cselect_b32 s64, s44, s14
	s_add_i32 s27, 0, 0x10000
	s_movk_i32 s66, 0xff80
	v_add_u32_e32 v121, s27, v7
	s_add_i32 s63, 0, 0x14000
	v_lshl_add_u64 v[178:179], s[50:51], 0, v[108:109]
	s_mov_b32 s67, -1
	ds_read_b128 v[110:113], v119
	ds_read_b128 v[114:117], v119 offset:1024
	ds_read_b128 v[122:125], v119 offset:2048
	ds_read_b128 v[126:129], v119 offset:3072
	ds_read_b128 v[130:133], v119 offset:4096
	ds_read_b128 v[134:137], v119 offset:5120
	ds_read_b128 v[138:141], v119 offset:6144
	ds_read_b128 v[142:145], v119 offset:7168
	ds_read_b128 v[146:149], v121
	ds_read_b128 v[150:153], v121 offset:1024
	ds_read_b128 v[154:157], v121 offset:2048
	ds_read_b128 v[158:161], v121 offset:3072
	v_add_u32_e32 v121, s63, v7
	v_lshl_add_u64 v[178:179], v[178:179], 0, s[66:67]
	s_add_i32 m0, s39, 0xc000
	ds_read_b128 v[162:165], v121
	ds_read_b128 v[166:169], v121 offset:1024
	ds_read_b128 v[170:173], v121 offset:2048
	ds_read_b128 v[174:177], v121 offset:3072
	global_load_lds_dwordx4 v[178:179], off
	s_waitcnt vmcnt(7)
	s_waitcnt lgkmcnt(0)
	s_barrier
	s_setprio 1
	s_waitcnt lgkmcnt(0)
	v_mfma_f32_16x16x32_bf16 v[100:103], v[146:149], v[110:113], v[100:103]
	v_mfma_f32_16x16x32_bf16 v[100:103], v[150:153], v[114:117], v[100:103]
	v_mfma_f32_16x16x32_bf16 v[92:95], v[146:149], v[122:125], v[92:95]
	v_mfma_f32_16x16x32_bf16 v[92:95], v[150:153], v[126:129], v[92:95]
	v_mfma_f32_16x16x32_bf16 v[72:75], v[146:149], v[130:133], v[72:75]
	v_mfma_f32_16x16x32_bf16 v[72:75], v[150:153], v[134:137], v[72:75]
	v_mfma_f32_16x16x32_bf16 v[56:59], v[146:149], v[138:141], v[56:59]
	v_mfma_f32_16x16x32_bf16 v[56:59], v[150:153], v[142:145], v[56:59]
	v_mfma_f32_16x16x32_bf16 v[96:99], v[154:157], v[110:113], v[96:99]
	v_mfma_f32_16x16x32_bf16 v[96:99], v[158:161], v[114:117], v[96:99]
	v_mfma_f32_16x16x32_bf16 v[80:83], v[154:157], v[122:125], v[80:83]
	v_mfma_f32_16x16x32_bf16 v[80:83], v[158:161], v[126:129], v[80:83]
	v_mfma_f32_16x16x32_bf16 v[64:67], v[154:157], v[130:133], v[64:67]
	v_mfma_f32_16x16x32_bf16 v[64:67], v[158:161], v[134:137], v[64:67]
	v_mfma_f32_16x16x32_bf16 v[48:51], v[154:157], v[138:141], v[48:51]
	v_mfma_f32_16x16x32_bf16 v[48:51], v[158:161], v[142:145], v[48:51]
	s_setprio 0
	s_setprio 1
	v_mfma_f32_16x16x32_bf16 v[88:91], v[162:165], v[110:113], v[88:91]
	v_mfma_f32_16x16x32_bf16 v[88:91], v[166:169], v[114:117], v[88:91]
	v_mfma_f32_16x16x32_bf16 v[76:79], v[162:165], v[122:125], v[76:79]
	v_mfma_f32_16x16x32_bf16 v[76:79], v[166:169], v[126:129], v[76:79]
	v_mfma_f32_16x16x32_bf16 v[60:63], v[162:165], v[130:133], v[60:63]
	v_mfma_f32_16x16x32_bf16 v[60:63], v[166:169], v[134:137], v[60:63]
	v_mfma_f32_16x16x32_bf16 v[44:47], v[162:165], v[138:141], v[44:47]
	v_mfma_f32_16x16x32_bf16 v[44:47], v[166:169], v[142:145], v[44:47]
	v_mfma_f32_16x16x32_bf16 v[84:87], v[170:173], v[110:113], v[84:87]
	v_mfma_f32_16x16x32_bf16 v[84:87], v[174:177], v[114:117], v[84:87]
	v_mfma_f32_16x16x32_bf16 v[68:71], v[170:173], v[122:125], v[68:71]
	v_mfma_f32_16x16x32_bf16 v[68:71], v[174:177], v[126:129], v[68:71]
	v_mfma_f32_16x16x32_bf16 v[52:55], v[170:173], v[130:133], v[52:55]
	v_mfma_f32_16x16x32_bf16 v[52:55], v[174:177], v[134:137], v[52:55]
	v_mfma_f32_16x16x32_bf16 v[40:43], v[170:173], v[138:141], v[40:43]
	v_mfma_f32_16x16x32_bf16 v[40:43], v[174:177], v[142:145], v[40:43]
	s_setprio 0
	s_barrier
	s_add_i32 s27, s27, s22
	v_lshl_add_u64 v[178:179], s[64:65], 0, v[2:3]
	s_mov_b32 m0, s27
	ds_read_b128 v[110:113], v120 offset:16384
	ds_read_b128 v[114:117], v120 offset:17408
	ds_read_b128 v[122:125], v120 offset:18432
	ds_read_b128 v[126:129], v120 offset:19456
	global_load_lds_dwordx4 v[178:179], off
	s_add_i32 m0, s27, 0x2000
	v_lshl_add_u64 v[180:181], s[64:65], 0, v[4:5]
	s_add_u32 s64, s64, s90
	s_addc_u32 s65, s65, 0
	s_add_i32 s27, s63, s22
	global_load_lds_dwordx4 v[180:181], off
	v_lshl_add_u64 v[182:183], s[64:65], 0, v[2:3]
	s_mov_b32 m0, s27
	v_lshl_add_u64 v[184:185], s[64:65], 0, v[4:5]
	global_load_lds_dwordx4 v[182:183], off
	s_add_i32 m0, s27, 0x2000
	v_lshl_add_u64 v[186:187], s[12:13], 0, v[106:107]
	global_load_lds_dwordx4 v[184:185], off
	s_mov_b32 m0, s39
	v_lshl_add_u64 v[188:189], s[12:13], 0, v[104:105]
	global_load_lds_dwordx4 v[186:187], off
	s_mov_b32 m0, s40
	s_nop 0
	global_load_lds_dwordx4 v[188:189], off
	s_waitcnt vmcnt(7)
	s_waitcnt lgkmcnt(0)
	s_barrier
	s_setprio 1
	s_waitcnt lgkmcnt(0)
	v_mfma_f32_16x16x32_bf16 v[36:39], v[146:149], v[110:113], v[36:39]
	v_mfma_f32_16x16x32_bf16 v[36:39], v[150:153], v[114:117], v[36:39]
	v_mfma_f32_16x16x32_bf16 v[20:23], v[146:149], v[122:125], v[20:23]
	v_mfma_f32_16x16x32_bf16 v[20:23], v[150:153], v[126:129], v[20:23]
	v_mfma_f32_16x16x32_bf16 v[32:35], v[154:157], v[110:113], v[32:35]
	v_mfma_f32_16x16x32_bf16 v[32:35], v[158:161], v[114:117], v[32:35]
	v_mfma_f32_16x16x32_bf16 v[16:19], v[154:157], v[122:125], v[16:19]
	v_mfma_f32_16x16x32_bf16 v[16:19], v[158:161], v[126:129], v[16:19]
	s_setprio 0
	s_setprio 1
	v_mfma_f32_16x16x32_bf16 v[28:31], v[162:165], v[110:113], v[28:31]
	v_mfma_f32_16x16x32_bf16 v[28:31], v[166:169], v[114:117], v[28:31]
	v_mfma_f32_16x16x32_bf16 v[12:15], v[162:165], v[122:125], v[12:15]
	v_mfma_f32_16x16x32_bf16 v[12:15], v[166:169], v[126:129], v[12:15]
	v_mfma_f32_16x16x32_bf16 v[24:27], v[170:173], v[110:113], v[24:27]
	v_mfma_f32_16x16x32_bf16 v[24:27], v[174:177], v[114:117], v[24:27]
	v_mfma_f32_16x16x32_bf16 v[8:11], v[170:173], v[122:125], v[8:11]
	v_mfma_f32_16x16x32_bf16 v[8:11], v[174:177], v[126:129], v[8:11]
	s_setprio 0
	s_barrier
	s_add_i32 s27, 0, 0x18000
	s_add_i32 s63, 0, 0x1c000
	s_add_u32 s12, s12, s90
	v_add_u32_e32 v121, s27, v7
	s_addc_u32 s13, s13, 0
	ds_read_b128 v[110:113], v119 offset:32768
	ds_read_b128 v[114:117], v119 offset:33792
	ds_read_b128 v[122:125], v119 offset:34816
	ds_read_b128 v[126:129], v119 offset:35840
	ds_read_b128 v[130:133], v119 offset:36864
	ds_read_b128 v[134:137], v119 offset:37888
	ds_read_b128 v[138:141], v119 offset:38912
	ds_read_b128 v[142:145], v119 offset:39936
	ds_read_b128 v[146:149], v121
	ds_read_b128 v[150:153], v121 offset:1024
	ds_read_b128 v[154:157], v121 offset:2048
	ds_read_b128 v[158:161], v121 offset:3072
	v_add_u32_e32 v121, s63, v7
	v_lshl_add_u64 v[190:191], s[12:13], 0, v[106:107]
	s_mov_b32 m0, s41
	ds_read_b128 v[162:165], v121
	ds_read_b128 v[166:169], v121 offset:1024
	ds_read_b128 v[170:173], v121 offset:2048
	ds_read_b128 v[174:177], v121 offset:3072
	global_load_lds_dwordx4 v[190:191], off
	s_waitcnt vmcnt(7)
	s_waitcnt lgkmcnt(0)
	s_barrier
	s_setprio 1
	s_waitcnt lgkmcnt(0)
	v_mfma_f32_16x16x32_bf16 v[100:103], v[146:149], v[110:113], v[100:103]
	v_mfma_f32_16x16x32_bf16 v[100:103], v[150:153], v[114:117], v[100:103]
	v_mfma_f32_16x16x32_bf16 v[92:95], v[146:149], v[122:125], v[92:95]
	v_mfma_f32_16x16x32_bf16 v[92:95], v[150:153], v[126:129], v[92:95]
	v_mfma_f32_16x16x32_bf16 v[72:75], v[146:149], v[130:133], v[72:75]
	v_mfma_f32_16x16x32_bf16 v[72:75], v[150:153], v[134:137], v[72:75]
	v_mfma_f32_16x16x32_bf16 v[56:59], v[146:149], v[138:141], v[56:59]
	v_mfma_f32_16x16x32_bf16 v[56:59], v[150:153], v[142:145], v[56:59]
	v_mfma_f32_16x16x32_bf16 v[96:99], v[154:157], v[110:113], v[96:99]
	v_mfma_f32_16x16x32_bf16 v[96:99], v[158:161], v[114:117], v[96:99]
	v_mfma_f32_16x16x32_bf16 v[80:83], v[154:157], v[122:125], v[80:83]
	v_mfma_f32_16x16x32_bf16 v[80:83], v[158:161], v[126:129], v[80:83]
	v_mfma_f32_16x16x32_bf16 v[64:67], v[154:157], v[130:133], v[64:67]
	v_mfma_f32_16x16x32_bf16 v[64:67], v[158:161], v[134:137], v[64:67]
	v_mfma_f32_16x16x32_bf16 v[48:51], v[154:157], v[138:141], v[48:51]
	v_mfma_f32_16x16x32_bf16 v[48:51], v[158:161], v[142:145], v[48:51]
	s_setprio 0
	s_setprio 1
	v_mfma_f32_16x16x32_bf16 v[88:91], v[162:165], v[110:113], v[88:91]
	v_mfma_f32_16x16x32_bf16 v[88:91], v[166:169], v[114:117], v[88:91]
	v_mfma_f32_16x16x32_bf16 v[76:79], v[162:165], v[122:125], v[76:79]
	v_mfma_f32_16x16x32_bf16 v[76:79], v[166:169], v[126:129], v[76:79]
	v_mfma_f32_16x16x32_bf16 v[60:63], v[162:165], v[130:133], v[60:63]
	v_mfma_f32_16x16x32_bf16 v[60:63], v[166:169], v[134:137], v[60:63]
	v_mfma_f32_16x16x32_bf16 v[44:47], v[162:165], v[138:141], v[44:47]
	v_mfma_f32_16x16x32_bf16 v[44:47], v[166:169], v[142:145], v[44:47]
	v_mfma_f32_16x16x32_bf16 v[84:87], v[170:173], v[110:113], v[84:87]
	v_mfma_f32_16x16x32_bf16 v[84:87], v[174:177], v[114:117], v[84:87]
	v_mfma_f32_16x16x32_bf16 v[68:71], v[170:173], v[122:125], v[68:71]
	v_mfma_f32_16x16x32_bf16 v[68:71], v[174:177], v[126:129], v[68:71]
	v_mfma_f32_16x16x32_bf16 v[52:55], v[170:173], v[130:133], v[52:55]
	v_mfma_f32_16x16x32_bf16 v[52:55], v[174:177], v[134:137], v[52:55]
	v_mfma_f32_16x16x32_bf16 v[40:43], v[170:173], v[138:141], v[40:43]
	v_mfma_f32_16x16x32_bf16 v[40:43], v[174:177], v[142:145], v[40:43]
	s_setprio 0
	s_barrier
	s_add_i32 s12, s27, s22
	v_lshl_add_u64 v[130:131], v[178:179], 0, s[0:1]
	s_mov_b32 m0, s12
	ds_read_b128 v[110:113], v120 offset:49152
	ds_read_b128 v[114:117], v120 offset:50176
	ds_read_b128 v[122:125], v120 offset:51200
	ds_read_b128 v[126:129], v120 offset:52224
	global_load_lds_dwordx4 v[130:131], off
	v_lshl_add_u64 v[130:131], v[180:181], 0, s[0:1]
	s_add_i32 m0, s12, 0x2000
	s_add_i32 s12, s63, s22
	global_load_lds_dwordx4 v[130:131], off
	v_lshl_add_u64 v[130:131], v[182:183], 0, s[0:1]
	s_mov_b32 m0, s12
	s_nop 0
	global_load_lds_dwordx4 v[130:131], off
	v_lshl_add_u64 v[130:131], v[184:185], 0, s[0:1]
	s_add_i32 m0, s12, 0x2000
	s_nop 0
	global_load_lds_dwordx4 v[130:131], off
	v_lshl_add_u64 v[130:131], v[186:187], 0, s[0:1]
	s_mov_b32 m0, s53
	s_nop 0
	global_load_lds_dwordx4 v[130:131], off
	v_lshl_add_u64 v[130:131], v[188:189], 0, s[0:1]
	s_mov_b32 m0, s54
	s_nop 0
	global_load_lds_dwordx4 v[130:131], off
	s_waitcnt vmcnt(7)
	s_waitcnt lgkmcnt(0)
	s_barrier
	s_setprio 1
	s_waitcnt lgkmcnt(0)
	v_mfma_f32_16x16x32_bf16 v[36:39], v[146:149], v[110:113], v[36:39]
	v_mfma_f32_16x16x32_bf16 v[36:39], v[150:153], v[114:117], v[36:39]
	v_mfma_f32_16x16x32_bf16 v[20:23], v[146:149], v[122:125], v[20:23]
	v_mfma_f32_16x16x32_bf16 v[20:23], v[150:153], v[126:129], v[20:23]
	v_mfma_f32_16x16x32_bf16 v[32:35], v[154:157], v[110:113], v[32:35]
	v_mfma_f32_16x16x32_bf16 v[32:35], v[158:161], v[114:117], v[32:35]
	v_mfma_f32_16x16x32_bf16 v[16:19], v[154:157], v[122:125], v[16:19]
	v_mfma_f32_16x16x32_bf16 v[16:19], v[158:161], v[126:129], v[16:19]
	s_setprio 0
	s_setprio 1
	v_mfma_f32_16x16x32_bf16 v[28:31], v[162:165], v[110:113], v[28:31]
	v_mfma_f32_16x16x32_bf16 v[28:31], v[166:169], v[114:117], v[28:31]
	v_mfma_f32_16x16x32_bf16 v[12:15], v[162:165], v[122:125], v[12:15]
	v_mfma_f32_16x16x32_bf16 v[12:15], v[166:169], v[126:129], v[12:15]
	v_mfma_f32_16x16x32_bf16 v[24:27], v[170:173], v[110:113], v[24:27]
	v_mfma_f32_16x16x32_bf16 v[24:27], v[174:177], v[114:117], v[24:27]
	v_mfma_f32_16x16x32_bf16 v[8:11], v[170:173], v[122:125], v[8:11]
	v_mfma_f32_16x16x32_bf16 v[8:11], v[174:177], v[126:129], v[8:11]
	s_setprio 0
	s_barrier
	s_add_u32 s50, s50, 0x100
	s_addc_u32 s51, s51, 0
	s_add_u32 s14, s14, 0x100
	s_addc_u32 s15, s15, 0
	s_cmp_ge_u32 s26, s55
	s_mov_b32 s12, s26
	s_cbranch_scc0 .LBB0_1482
	s_and_b64 vcc, exec, s[36:37]
	s_cbranch_vccz .LBB0_1485
	s_barrier
